# p4+p5: de-staggered tile epilogues (both wave groups run the gate/residual epilogue concurrently)
# speedup vs baseline: 1.0116x; 1.0014x over previous
; DI unsigned pk2(float lo, float hi) { f32x2 v = {lo, hi}; bf16x2_t b = __builtin_convertvector(v, bf16x2_t); return __builtin_bit_cast(unsigned, b); }
; DI float lo16(unsigned u) { return __uint_as_float(u << 16); }
; DI float hi16(unsigned u) { return __uint_as_float(u & 0xffff0000u); }
; DI float sigmoidf_(float x) { return __builtin_amdgcn_rcpf(1.f + __expf(-x)); }
;     DI void operator()(const f32x4 (&acc)[2][2][4][2], const Unit& u, int wr, int wc, int fr, int fq) const {
;         const int row0 = u.pm * BM + wr * 64 + fr, col0 = u.pn * BM + wc * 32 + 8 * fq;
;         u32x4 gn[2][4][2];
; #pragma unroll
;         for (int ai = 0; ai < 2; ++ai)
; #pragma unroll
;             for (int m = 0; m < 4; ++m) { const bf16_t* rowp = P + (size_t)(row0 + ai * HALF + m * 16) * LDP + col0;
; #pragma unroll
;                 for (int bj = 0; bj < 2; ++bj) gn[ai][m][bj] = *(const u32x4*)(rowp + bj * HALF + C_GLN); }
; #pragma unroll
;         for (int ai = 0; ai < 2; ++ai)
; #pragma unroll
;             for (int m = 0; m < 4; ++m) { bf16_t* rowp = P + (size_t)(row0 + ai * HALF + m * 16) * LDP + col0;
; #pragma unroll
;                 for (int bj = 0; bj < 2; ++bj) { const f32x4 v0 = acc[ai][bj][m][0], v1 = acc[ai][bj][m][1];
;                     const unsigned gnw[4] = {gn[ai][m][bj].x, gn[ai][m][bj].y, gn[ai][m][bj].z, gn[ai][m][bj].w};
;                     const float o[8] = {v0[0], v0[1], v0[2], v0[3], v1[0], v1[1], v1[2], v1[3]};
;                     u32x4 w;
;                     w.x = pk2(o[0] * sigmoidf_(lo16(gnw[0])), o[1] * sigmoidf_(hi16(gnw[0]))); w.y = pk2(o[2] * sigmoidf_(lo16(gnw[1])), o[3] * sigmoidf_(hi16(gnw[1])));
;                     w.z = pk2(o[4] * sigmoidf_(lo16(gnw[2])), o[5] * sigmoidf_(hi16(gnw[2]))); w.w = pk2(o[6] * sigmoidf_(lo16(gnw[3])), o[7] * sigmoidf_(hi16(gnw[3])));
;                     *(u32x4*)(rowp + bj * HALF) = w; } }
;     }
.LBB0_622:
	s_cmpk_gt_u32 s42, 0xff
	s_cbranch_scc1 .Lp4_e0
	s_barrier
.Lp4_e0:
	v_ashrrev_i32_e32 v205, 31, v204
	v_lshlrev_b64 v[2:3], 1, v[204:205]
	v_lshl_add_u64 v[132:133], s[30:31], 0, v[2:3]
	v_mad_i64_i32 v[134:135], s[0:1], v223, s54, v[132:133]
	v_add_co_u32_e32 v134, vcc, 0x6000, v134
	v_mov_b64_e32 v[204:205], s[30:31]
	s_nop 0
	v_addc_co_u32_e32 v135, vcc, 0, v135, vcc
	global_load_dwordx4 v[210:213], v[134:135], off offset:1024
	global_load_dwordx4 v[224:227], v[134:135], off offset:1280
	v_or_b32_e32 v214, 16, v223
	v_mad_i64_i32 v[136:137], s[0:1], v223, s54, v[204:205]
	v_lshl_add_u64 v[228:229], v[136:137], 0, v[2:3]
	v_mad_i64_i32 v[136:137], s[0:1], v214, s54, v[132:133]
	v_add_co_u32_e32 v136, vcc, 0x6000, v136
	v_or_b32_e32 v216, 32, v223
	s_nop 0
	v_addc_co_u32_e32 v137, vcc, 0, v137, vcc
	global_load_dwordx4 v[184:187], v[136:137], off offset:1024
	global_load_dwordx4 v[180:183], v[136:137], off offset:1280
	v_mad_i64_i32 v[138:139], s[0:1], v216, s54, v[132:133]
	v_or_b32_e32 v209, 48, v223
	v_add_co_u32_e32 v134, vcc, 0x6000, v138
	v_mad_i64_i32 v[140:141], s[0:1], v209, s54, v[132:133]
	s_nop 0
	v_addc_co_u32_e32 v135, vcc, 0, v139, vcc
	v_add_u32_e32 v208, 0x80, v223
	v_add_co_u32_e32 v136, vcc, 0x6000, v140
	v_mad_i64_i32 v[142:143], s[0:1], v208, s54, v[132:133]
	s_nop 0
	v_addc_co_u32_e32 v137, vcc, 0, v141, vcc
	v_add_u32_e32 v207, 0x90, v223
	global_load_dwordx4 v[176:179], v[134:135], off offset:1024
	global_load_dwordx4 v[172:175], v[134:135], off offset:1280
	v_add_co_u32_e32 v134, vcc, 0x6000, v142
	v_mad_i64_i32 v[144:145], s[0:1], v207, s54, v[132:133]
	s_nop 0
	v_addc_co_u32_e32 v135, vcc, 0, v143, vcc
	v_add_u32_e32 v206, 0xa0, v223
	global_load_dwordx4 v[168:171], v[136:137], off offset:1024
	global_load_dwordx4 v[164:167], v[136:137], off offset:1280
	v_add_co_u32_e32 v136, vcc, 0x6000, v144
	v_mad_i64_i32 v[146:147], s[0:1], v206, s54, v[132:133]
	s_nop 0
	v_addc_co_u32_e32 v137, vcc, 0, v145, vcc
	global_load_dwordx4 v[160:163], v[134:135], off offset:1024
	global_load_dwordx4 v[156:159], v[134:135], off offset:1280
	v_add_co_u32_e32 v134, vcc, 0x6000, v146
	global_load_dwordx4 v[152:155], v[136:137], off offset:1024
	global_load_dwordx4 v[148:151], v[136:137], off offset:1280
	v_addc_co_u32_e32 v135, vcc, 0, v147, vcc
	global_load_dwordx4 v[144:147], v[134:135], off offset:1024
	global_load_dwordx4 v[140:143], v[134:135], off offset:1280
	v_add_u32_e32 v1, 0xb0, v223
	v_mad_i64_i32 v[132:133], s[0:1], v1, s54, v[132:133]
	v_add_co_u32_e32 v132, vcc, 0x6000, v132
	s_mov_b32 s37, s18
	s_nop 0
	v_addc_co_u32_e32 v133, vcc, 0, v133, vcc
	s_and_b64 vcc, exec, s[2:3]
	s_mov_b32 s36, s20
	s_mov_b64 s[38:39], s[24:25]
	s_mov_b64 s[26:27], s[22:23]
	s_waitcnt vmcnt(0)
	v_lshlrev_b32_e32 v134, 16, v210
	v_and_b32_e32 v135, 0xffff0000, v210
	v_mul_f32_e32 v134, 0xbfb8aa3b, v134
	v_mul_f32_e32 v135, 0xbfb8aa3b, v135
	v_exp_f32_e32 v210, v134
	v_exp_f32_e32 v218, v135
	global_load_dwordx4 v[136:139], v[132:133], off offset:1024
	s_nop 0
	global_load_dwordx4 v[132:135], v[132:133], off offset:1280
	v_add_f32_e32 v210, 1.0, v210
	v_rcp_f32_e32 v230, v210
	v_add_f32_e32 v210, 1.0, v218
	v_rcp_f32_e32 v231, v210
	v_lshlrev_b32_e32 v210, 16, v211
	v_and_b32_e32 v211, 0xffff0000, v211
	v_mul_f32_e32 v210, 0xbfb8aa3b, v210
	v_mul_f32_e32 v211, 0xbfb8aa3b, v211
	v_exp_f32_e32 v210, v210
	v_exp_f32_e32 v211, v211
	v_lshlrev_b32_e32 v218, 16, v212
	v_and_b32_e32 v212, 0xffff0000, v212
	v_add_f32_e32 v210, 1.0, v210
	v_add_f32_e32 v211, 1.0, v211
	v_rcp_f32_e32 v210, v210
	v_rcp_f32_e32 v211, v211
	v_mul_f32_e32 v218, 0xbfb8aa3b, v218
	v_mul_f32_e32 v212, 0xbfb8aa3b, v212
	v_exp_f32_e32 v218, v218
	v_exp_f32_e32 v212, v212
	v_pk_mul_f32 v[128:129], v[128:129], v[230:231]
	v_pk_mul_f32 v[130:131], v[130:131], v[210:211]
	v_cvt_pk_bf16_f32 v128, v128, v129
	v_cvt_pk_bf16_f32 v129, v130, v131
	v_lshlrev_b32_e32 v130, 16, v213
	v_add_f32_e32 v218, 1.0, v218
	v_add_f32_e32 v212, 1.0, v212
	v_mul_f32_e32 v130, 0xbfb8aa3b, v130
	v_rcp_f32_e32 v230, v218
	v_rcp_f32_e32 v231, v212
	v_exp_f32_e32 v131, v130
	v_and_b32_e32 v130, 0xffff0000, v213
	v_mul_f32_e32 v130, 0xbfb8aa3b, v130
	v_exp_f32_e32 v210, v130
	v_pk_mul_f32 v[124:125], v[124:125], v[230:231]
	s_nop 0
	v_cvt_pk_bf16_f32 v130, v124, v125
	v_add_f32_e32 v124, 1.0, v131
	v_lshlrev_b32_e32 v131, 16, v224
	v_add_f32_e32 v125, 1.0, v210
	v_mul_f32_e32 v131, 0xbfb8aa3b, v131
	v_and_b32_e32 v210, 0xffff0000, v224
	v_exp_f32_e32 v131, v131
	v_mul_f32_e32 v210, 0xbfb8aa3b, v210
	v_rcp_f32_e32 v124, v124
	v_exp_f32_e32 v211, v210
	v_rcp_f32_e32 v125, v125
	v_add_f32_e32 v131, 1.0, v131
	v_rcp_f32_e32 v210, v131
	v_add_f32_e32 v131, 1.0, v211
	v_pk_mul_f32 v[124:125], v[126:127], v[124:125]
	v_rcp_f32_e32 v211, v131
	v_cvt_pk_bf16_f32 v131, v124, v125
	v_lshlrev_b32_e32 v124, 16, v225
	v_mul_f32_e32 v124, 0xbfb8aa3b, v124
	v_and_b32_e32 v125, 0xffff0000, v225
	v_exp_f32_e32 v124, v124
	v_mul_f32_e32 v125, 0xbfb8aa3b, v125
	v_exp_f32_e32 v125, v125
	v_pk_mul_f32 v[120:121], v[120:121], v[210:211]
	v_and_b32_e32 v126, 0xffff0000, v226
	v_cvt_pk_bf16_f32 v120, v120, v121
	v_add_f32_e32 v121, 1.0, v124
	v_rcp_f32_e32 v124, v121
	v_add_f32_e32 v121, 1.0, v125
	v_rcp_f32_e32 v125, v121
	v_lshlrev_b32_e32 v121, 16, v226
	v_mul_f32_e32 v121, 0xbfb8aa3b, v121
	v_exp_f32_e32 v121, v121
	v_mul_f32_e32 v126, 0xbfb8aa3b, v126
	v_exp_f32_e32 v126, v126
	v_pk_mul_f32 v[122:123], v[122:123], v[124:125]
	v_lshlrev_b32_e32 v125, 16, v227
	v_add_f32_e32 v121, 1.0, v121
	v_mul_f32_e32 v125, 0xbfb8aa3b, v125
	v_rcp_f32_e32 v124, v121
	v_add_f32_e32 v121, 1.0, v126
	v_exp_f32_e32 v126, v125
; DI unsigned pk2(float lo, float hi) { f32x2 v = {lo, hi}; bf16x2_t b = __builtin_convertvector(v, bf16x2_t); return __builtin_bit_cast(unsigned, b); }
; DI float lo16(unsigned u) { return __uint_as_float(u << 16); }
; DI float hi16(unsigned u) { return __uint_as_float(u & 0xffff0000u); }
; DI float sigmoidf_(float x) { return __builtin_amdgcn_rcpf(1.f + __expf(-x)); }
;     DI void operator()(const f32x4 (&acc)[2][2][4][2], const Unit& u, int wr, int wc, int fr, int fq) const {
;     ...
; #pragma unroll
;         for (int ai = 0; ai < 2; ++ai)
; #pragma unroll
;             for (int m = 0; m < 4; ++m) { bf16_t* rowp = P + (size_t)(row0 + ai * HALF + m * 16) * LDP + col0;
; #pragma unroll
;                 for (int bj = 0; bj < 2; ++bj) { const f32x4 v0 = acc[ai][bj][m][0], v1 = acc[ai][bj][m][1];
;                     const unsigned gnw[4] = {gn[ai][m][bj].x, gn[ai][m][bj].y, gn[ai][m][bj].z, gn[ai][m][bj].w};
;                     const float o[8] = {v0[0], v0[1], v0[2], v0[3], v1[0], v1[1], v1[2], v1[3]};
;                     u32x4 w;
;                     w.x = pk2(o[0] * sigmoidf_(lo16(gnw[0])), o[1] * sigmoidf_(hi16(gnw[0]))); w.y = pk2(o[2] * sigmoidf_(lo16(gnw[1])), o[3] * sigmoidf_(hi16(gnw[1])));
;                     w.z = pk2(o[4] * sigmoidf_(lo16(gnw[2])), o[5] * sigmoidf_(hi16(gnw[2]))); w.w = pk2(o[6] * sigmoidf_(lo16(gnw[3])), o[7] * sigmoidf_(hi16(gnw[3])));
;                     *(u32x4*)(rowp + bj * HALF) = w; } }
	v_and_b32_e32 v125, 0xffff0000, v227
	v_mul_f32_e32 v125, 0xbfb8aa3b, v125
	v_exp_f32_e32 v127, v125
	v_rcp_f32_e32 v125, v121
	v_add_f32_e32 v121, 1.0, v126
	v_rcp_f32_e32 v126, v121
	v_add_f32_e32 v121, 1.0, v127
	v_rcp_f32_e32 v127, v121
	v_pk_mul_f32 v[116:117], v[116:117], v[124:125]
	v_cvt_pk_bf16_f32 v121, v122, v123
	v_cvt_pk_bf16_f32 v122, v116, v117
	v_pk_mul_f32 v[116:117], v[118:119], v[126:127]
	v_lshlrev_b32_e32 v118, 16, v184
	v_and_b32_e32 v119, 0xffff0000, v184
	v_mul_f32_e32 v118, 0xbfb8aa3b, v118
	v_mul_f32_e32 v119, 0xbfb8aa3b, v119
	v_exp_f32_e32 v118, v118
	v_exp_f32_e32 v119, v119
	v_cvt_pk_bf16_f32 v123, v116, v117
	global_store_dwordx4 v[228:229], v[120:123], off offset:256
	v_add_f32_e32 v118, 1.0, v118
	v_add_f32_e32 v119, 1.0, v119
	v_lshlrev_b32_e32 v120, 16, v185
	v_and_b32_e32 v121, 0xffff0000, v185
	v_mul_f32_e32 v120, 0xbfb8aa3b, v120
	v_mul_f32_e32 v121, 0xbfb8aa3b, v121
	v_rcp_f32_e32 v118, v118
	v_rcp_f32_e32 v119, v119
	v_exp_f32_e32 v120, v120
	v_exp_f32_e32 v121, v121
	v_mad_i64_i32 v[116:117], s[0:1], v214, s54, v[204:205]
	v_pk_mul_f32 v[112:113], v[112:113], v[118:119]
	v_add_f32_e32 v118, 1.0, v120
	v_add_f32_e32 v119, 1.0, v121
	v_rcp_f32_e32 v118, v118
	v_lshlrev_b32_e32 v120, 16, v186
	v_and_b32_e32 v121, 0xffff0000, v186
	v_rcp_f32_e32 v119, v119
	v_mul_f32_e32 v120, 0xbfb8aa3b, v120
	v_mul_f32_e32 v121, 0xbfb8aa3b, v121
	v_exp_f32_e32 v120, v120
	v_exp_f32_e32 v121, v121
	v_pk_mul_f32 v[114:115], v[114:115], v[118:119]
	v_cvt_pk_bf16_f32 v112, v112, v113
	v_cvt_pk_bf16_f32 v113, v114, v115
	v_lshlrev_b32_e32 v114, 16, v187
	v_add_f32_e32 v120, 1.0, v120
	v_add_f32_e32 v121, 1.0, v121
	v_mul_f32_e32 v114, 0xbfb8aa3b, v114
	v_rcp_f32_e32 v120, v120
	v_rcp_f32_e32 v121, v121
	v_exp_f32_e32 v115, v114
	v_and_b32_e32 v114, 0xffff0000, v187
	v_mul_f32_e32 v114, 0xbfb8aa3b, v114
	v_exp_f32_e32 v118, v114
	v_pk_mul_f32 v[108:109], v[108:109], v[120:121]
	v_lshl_add_u64 v[116:117], v[116:117], 0, v[2:3]
	v_cvt_pk_bf16_f32 v114, v108, v109
	v_add_f32_e32 v108, 1.0, v115
	v_lshlrev_b32_e32 v115, 16, v180
	v_add_f32_e32 v109, 1.0, v118
	v_mul_f32_e32 v115, 0xbfb8aa3b, v115
	v_and_b32_e32 v118, 0xffff0000, v180
	v_exp_f32_e32 v115, v115
	v_mul_f32_e32 v118, 0xbfb8aa3b, v118
	v_rcp_f32_e32 v108, v108
	v_exp_f32_e32 v119, v118
	v_rcp_f32_e32 v109, v109
	v_add_f32_e32 v115, 1.0, v115
	v_rcp_f32_e32 v118, v115
	v_add_f32_e32 v115, 1.0, v119
	v_pk_mul_f32 v[108:109], v[110:111], v[108:109]
	v_rcp_f32_e32 v119, v115
	v_cvt_pk_bf16_f32 v115, v108, v109
	v_lshlrev_b32_e32 v108, 16, v181
	v_mul_f32_e32 v108, 0xbfb8aa3b, v108
	v_and_b32_e32 v109, 0xffff0000, v181
	v_exp_f32_e32 v108, v108
	v_mul_f32_e32 v109, 0xbfb8aa3b, v109
	v_exp_f32_e32 v109, v109
	v_pk_mul_f32 v[104:105], v[104:105], v[118:119]
	v_and_b32_e32 v110, 0xffff0000, v182
	v_cvt_pk_bf16_f32 v104, v104, v105
	v_add_f32_e32 v105, 1.0, v108
	v_rcp_f32_e32 v108, v105
	v_add_f32_e32 v105, 1.0, v109
	v_rcp_f32_e32 v109, v105
	v_lshlrev_b32_e32 v105, 16, v182
	v_mul_f32_e32 v105, 0xbfb8aa3b, v105
	v_exp_f32_e32 v105, v105
	v_mul_f32_e32 v110, 0xbfb8aa3b, v110
	v_exp_f32_e32 v110, v110
	v_pk_mul_f32 v[106:107], v[106:107], v[108:109]
	v_lshlrev_b32_e32 v109, 16, v183
	v_add_f32_e32 v105, 1.0, v105
	v_mul_f32_e32 v109, 0xbfb8aa3b, v109
	v_rcp_f32_e32 v108, v105
	v_add_f32_e32 v105, 1.0, v110
	v_exp_f32_e32 v110, v109
	v_and_b32_e32 v109, 0xffff0000, v183
	v_mul_f32_e32 v109, 0xbfb8aa3b, v109
	v_exp_f32_e32 v111, v109
	v_rcp_f32_e32 v109, v105
	v_add_f32_e32 v105, 1.0, v110
	v_rcp_f32_e32 v110, v105
	v_add_f32_e32 v105, 1.0, v111
	v_rcp_f32_e32 v111, v105
	v_pk_mul_f32 v[100:101], v[100:101], v[108:109]
	v_cvt_pk_bf16_f32 v105, v106, v107
	v_cvt_pk_bf16_f32 v106, v100, v101
	v_pk_mul_f32 v[100:101], v[102:103], v[110:111]
	v_lshlrev_b32_e32 v102, 16, v176
	v_and_b32_e32 v103, 0xffff0000, v176
	v_mul_f32_e32 v102, 0xbfb8aa3b, v102
	v_mul_f32_e32 v103, 0xbfb8aa3b, v103
	v_exp_f32_e32 v102, v102
	v_exp_f32_e32 v103, v103
	v_cvt_pk_bf16_f32 v107, v100, v101
	global_store_dwordx4 v[116:117], v[104:107], off offset:256
	v_add_f32_e32 v102, 1.0, v102
	v_add_f32_e32 v103, 1.0, v103
	v_lshlrev_b32_e32 v104, 16, v177
	v_and_b32_e32 v105, 0xffff0000, v177
	v_mul_f32_e32 v104, 0xbfb8aa3b, v104
	v_mul_f32_e32 v105, 0xbfb8aa3b, v105
	v_rcp_f32_e32 v102, v102
	v_rcp_f32_e32 v103, v103
	v_exp_f32_e32 v104, v104
	v_exp_f32_e32 v105, v105
	v_mad_i64_i32 v[100:101], s[0:1], v216, s54, v[204:205]
	v_pk_mul_f32 v[96:97], v[96:97], v[102:103]
	v_add_f32_e32 v102, 1.0, v104
	v_add_f32_e32 v103, 1.0, v105
	v_rcp_f32_e32 v102, v102
	v_lshlrev_b32_e32 v104, 16, v178
	v_and_b32_e32 v105, 0xffff0000, v178
	v_rcp_f32_e32 v103, v103
	v_mul_f32_e32 v104, 0xbfb8aa3b, v104
	v_mul_f32_e32 v105, 0xbfb8aa3b, v105
	v_exp_f32_e32 v104, v104
	v_exp_f32_e32 v105, v105
	v_pk_mul_f32 v[98:99], v[98:99], v[102:103]
	v_cvt_pk_bf16_f32 v96, v96, v97
	v_cvt_pk_bf16_f32 v97, v98, v99
	v_lshlrev_b32_e32 v98, 16, v179
	v_add_f32_e32 v104, 1.0, v104
	v_add_f32_e32 v105, 1.0, v105
	v_mul_f32_e32 v98, 0xbfb8aa3b, v98
	v_rcp_f32_e32 v104, v104
	v_rcp_f32_e32 v105, v105
	v_exp_f32_e32 v99, v98
	v_and_b32_e32 v98, 0xffff0000, v179
	v_mul_f32_e32 v98, 0xbfb8aa3b, v98
	v_exp_f32_e32 v102, v98
	v_pk_mul_f32 v[92:93], v[92:93], v[104:105]
	v_lshl_add_u64 v[100:101], v[100:101], 0, v[2:3]
	v_cvt_pk_bf16_f32 v98, v92, v93
	v_add_f32_e32 v92, 1.0, v99
	v_lshlrev_b32_e32 v99, 16, v172
	v_add_f32_e32 v93, 1.0, v102
	v_mul_f32_e32 v99, 0xbfb8aa3b, v99
	v_and_b32_e32 v102, 0xffff0000, v172
	v_exp_f32_e32 v99, v99
	v_mul_f32_e32 v102, 0xbfb8aa3b, v102
	v_rcp_f32_e32 v92, v92
	v_exp_f32_e32 v103, v102
	v_rcp_f32_e32 v93, v93
; DI unsigned pk2(float lo, float hi) { f32x2 v = {lo, hi}; bf16x2_t b = __builtin_convertvector(v, bf16x2_t); return __builtin_bit_cast(unsigned, b); }
; DI float lo16(unsigned u) { return __uint_as_float(u << 16); }
; DI float hi16(unsigned u) { return __uint_as_float(u & 0xffff0000u); }
; DI float sigmoidf_(float x) { return __builtin_amdgcn_rcpf(1.f + __expf(-x)); }
;     DI void operator()(const f32x4 (&acc)[2][2][4][2], const Unit& u, int wr, int wc, int fr, int fq) const {
;     ...
; #pragma unroll
;         for (int ai = 0; ai < 2; ++ai)
; #pragma unroll
;             for (int m = 0; m < 4; ++m) { bf16_t* rowp = P + (size_t)(row0 + ai * HALF + m * 16) * LDP + col0;
; #pragma unroll
;                 for (int bj = 0; bj < 2; ++bj) { const f32x4 v0 = acc[ai][bj][m][0], v1 = acc[ai][bj][m][1];
;                     const unsigned gnw[4] = {gn[ai][m][bj].x, gn[ai][m][bj].y, gn[ai][m][bj].z, gn[ai][m][bj].w};
;                     const float o[8] = {v0[0], v0[1], v0[2], v0[3], v1[0], v1[1], v1[2], v1[3]};
;                     u32x4 w;
;                     w.x = pk2(o[0] * sigmoidf_(lo16(gnw[0])), o[1] * sigmoidf_(hi16(gnw[0]))); w.y = pk2(o[2] * sigmoidf_(lo16(gnw[1])), o[3] * sigmoidf_(hi16(gnw[1])));
;                     w.z = pk2(o[4] * sigmoidf_(lo16(gnw[2])), o[5] * sigmoidf_(hi16(gnw[2]))); w.w = pk2(o[6] * sigmoidf_(lo16(gnw[3])), o[7] * sigmoidf_(hi16(gnw[3])));
;                     *(u32x4*)(rowp + bj * HALF) = w; } }
	v_add_f32_e32 v99, 1.0, v99
	v_rcp_f32_e32 v102, v99
	v_add_f32_e32 v99, 1.0, v103
	v_pk_mul_f32 v[92:93], v[94:95], v[92:93]
	v_rcp_f32_e32 v103, v99
	v_cvt_pk_bf16_f32 v99, v92, v93
	v_lshlrev_b32_e32 v92, 16, v173
	v_mul_f32_e32 v92, 0xbfb8aa3b, v92
	v_and_b32_e32 v93, 0xffff0000, v173
	v_exp_f32_e32 v92, v92
	v_mul_f32_e32 v93, 0xbfb8aa3b, v93
	v_exp_f32_e32 v93, v93
	v_pk_mul_f32 v[88:89], v[88:89], v[102:103]
	v_and_b32_e32 v94, 0xffff0000, v174
	v_cvt_pk_bf16_f32 v88, v88, v89
	v_add_f32_e32 v89, 1.0, v92
	v_rcp_f32_e32 v92, v89
	v_add_f32_e32 v89, 1.0, v93
	v_rcp_f32_e32 v93, v89
	v_lshlrev_b32_e32 v89, 16, v174
	v_mul_f32_e32 v89, 0xbfb8aa3b, v89
	v_exp_f32_e32 v89, v89
	v_mul_f32_e32 v94, 0xbfb8aa3b, v94
	v_exp_f32_e32 v94, v94
	v_pk_mul_f32 v[90:91], v[90:91], v[92:93]
	v_lshlrev_b32_e32 v93, 16, v175
	v_add_f32_e32 v89, 1.0, v89
	v_mul_f32_e32 v93, 0xbfb8aa3b, v93
	v_rcp_f32_e32 v92, v89
	v_add_f32_e32 v89, 1.0, v94
	v_exp_f32_e32 v94, v93
	v_and_b32_e32 v93, 0xffff0000, v175
	v_mul_f32_e32 v93, 0xbfb8aa3b, v93
	v_exp_f32_e32 v95, v93
	v_rcp_f32_e32 v93, v89
	v_add_f32_e32 v89, 1.0, v94
	v_rcp_f32_e32 v94, v89
	v_add_f32_e32 v89, 1.0, v95
	v_rcp_f32_e32 v95, v89
	v_pk_mul_f32 v[84:85], v[84:85], v[92:93]
	v_cvt_pk_bf16_f32 v89, v90, v91
	v_cvt_pk_bf16_f32 v90, v84, v85
	v_pk_mul_f32 v[84:85], v[86:87], v[94:95]
	v_lshlrev_b32_e32 v86, 16, v168
	v_and_b32_e32 v87, 0xffff0000, v168
	v_mul_f32_e32 v86, 0xbfb8aa3b, v86
	v_mul_f32_e32 v87, 0xbfb8aa3b, v87
	v_exp_f32_e32 v86, v86
	v_exp_f32_e32 v87, v87
	v_cvt_pk_bf16_f32 v91, v84, v85
	global_store_dwordx4 v[100:101], v[88:91], off offset:256
	v_add_f32_e32 v86, 1.0, v86
	v_add_f32_e32 v87, 1.0, v87
	v_lshlrev_b32_e32 v88, 16, v169
	v_and_b32_e32 v89, 0xffff0000, v169
	v_mul_f32_e32 v88, 0xbfb8aa3b, v88
	v_mul_f32_e32 v89, 0xbfb8aa3b, v89
	v_rcp_f32_e32 v86, v86
	v_rcp_f32_e32 v87, v87
	v_exp_f32_e32 v88, v88
	v_exp_f32_e32 v89, v89
	v_mad_i64_i32 v[84:85], s[0:1], v209, s54, v[204:205]
	v_pk_mul_f32 v[80:81], v[80:81], v[86:87]
	v_add_f32_e32 v86, 1.0, v88
	v_add_f32_e32 v87, 1.0, v89
	v_rcp_f32_e32 v86, v86
	v_lshlrev_b32_e32 v88, 16, v170
	v_and_b32_e32 v89, 0xffff0000, v170
	v_rcp_f32_e32 v87, v87
	v_mul_f32_e32 v88, 0xbfb8aa3b, v88
	v_mul_f32_e32 v89, 0xbfb8aa3b, v89
	v_exp_f32_e32 v88, v88
	v_exp_f32_e32 v89, v89
	v_pk_mul_f32 v[82:83], v[82:83], v[86:87]
	v_cvt_pk_bf16_f32 v80, v80, v81
	v_cvt_pk_bf16_f32 v81, v82, v83
	v_lshlrev_b32_e32 v82, 16, v171
	v_add_f32_e32 v88, 1.0, v88
	v_add_f32_e32 v89, 1.0, v89
	v_mul_f32_e32 v82, 0xbfb8aa3b, v82
	v_rcp_f32_e32 v88, v88
	v_rcp_f32_e32 v89, v89
	v_exp_f32_e32 v83, v82
	v_and_b32_e32 v82, 0xffff0000, v171
	v_mul_f32_e32 v82, 0xbfb8aa3b, v82
	v_exp_f32_e32 v86, v82
	v_pk_mul_f32 v[76:77], v[76:77], v[88:89]
	v_lshl_add_u64 v[84:85], v[84:85], 0, v[2:3]
	v_cvt_pk_bf16_f32 v82, v76, v77
	v_add_f32_e32 v76, 1.0, v83
	v_lshlrev_b32_e32 v83, 16, v164
	v_add_f32_e32 v77, 1.0, v86
	v_mul_f32_e32 v83, 0xbfb8aa3b, v83
	v_and_b32_e32 v86, 0xffff0000, v164
	v_exp_f32_e32 v83, v83
	v_mul_f32_e32 v86, 0xbfb8aa3b, v86
	v_rcp_f32_e32 v76, v76
	v_exp_f32_e32 v87, v86
	v_rcp_f32_e32 v77, v77
	v_add_f32_e32 v83, 1.0, v83
	v_rcp_f32_e32 v86, v83
	v_add_f32_e32 v83, 1.0, v87
	v_pk_mul_f32 v[76:77], v[78:79], v[76:77]
	v_rcp_f32_e32 v87, v83
	v_cvt_pk_bf16_f32 v83, v76, v77
	v_lshlrev_b32_e32 v76, 16, v165
	v_mul_f32_e32 v76, 0xbfb8aa3b, v76
	v_and_b32_e32 v77, 0xffff0000, v165
	v_exp_f32_e32 v76, v76
	v_mul_f32_e32 v77, 0xbfb8aa3b, v77
	v_exp_f32_e32 v77, v77
	v_pk_mul_f32 v[72:73], v[72:73], v[86:87]
	v_and_b32_e32 v78, 0xffff0000, v166
	v_cvt_pk_bf16_f32 v72, v72, v73
	v_add_f32_e32 v73, 1.0, v76
	v_rcp_f32_e32 v76, v73
	v_add_f32_e32 v73, 1.0, v77
	v_rcp_f32_e32 v77, v73
	v_lshlrev_b32_e32 v73, 16, v166
	v_mul_f32_e32 v73, 0xbfb8aa3b, v73
	v_exp_f32_e32 v73, v73
	v_mul_f32_e32 v78, 0xbfb8aa3b, v78
	v_exp_f32_e32 v78, v78
	v_pk_mul_f32 v[74:75], v[74:75], v[76:77]
	v_lshlrev_b32_e32 v77, 16, v167
	v_add_f32_e32 v73, 1.0, v73
	v_mul_f32_e32 v77, 0xbfb8aa3b, v77
	v_rcp_f32_e32 v76, v73
	v_add_f32_e32 v73, 1.0, v78
	v_exp_f32_e32 v78, v77
	v_and_b32_e32 v77, 0xffff0000, v167
	v_mul_f32_e32 v77, 0xbfb8aa3b, v77
	v_exp_f32_e32 v79, v77
	v_rcp_f32_e32 v77, v73
	v_add_f32_e32 v73, 1.0, v78
	v_rcp_f32_e32 v78, v73
	v_add_f32_e32 v73, 1.0, v79
	v_rcp_f32_e32 v79, v73
	v_pk_mul_f32 v[68:69], v[68:69], v[76:77]
	v_cvt_pk_bf16_f32 v73, v74, v75
	v_cvt_pk_bf16_f32 v74, v68, v69
	v_pk_mul_f32 v[68:69], v[70:71], v[78:79]
	v_lshlrev_b32_e32 v70, 16, v160
	v_and_b32_e32 v71, 0xffff0000, v160
	v_mul_f32_e32 v70, 0xbfb8aa3b, v70
	v_mul_f32_e32 v71, 0xbfb8aa3b, v71
	v_exp_f32_e32 v70, v70
	v_exp_f32_e32 v71, v71
	v_cvt_pk_bf16_f32 v75, v68, v69
	global_store_dwordx4 v[84:85], v[72:75], off offset:256
	v_add_f32_e32 v70, 1.0, v70
	v_add_f32_e32 v71, 1.0, v71
	v_lshlrev_b32_e32 v72, 16, v161
	v_and_b32_e32 v73, 0xffff0000, v161
	v_mul_f32_e32 v72, 0xbfb8aa3b, v72
	v_mul_f32_e32 v73, 0xbfb8aa3b, v73
	v_rcp_f32_e32 v70, v70
	v_rcp_f32_e32 v71, v71
	v_exp_f32_e32 v72, v72
	v_exp_f32_e32 v73, v73
	v_mad_i64_i32 v[68:69], s[0:1], v208, s54, v[204:205]
	v_pk_mul_f32 v[64:65], v[64:65], v[70:71]
	v_add_f32_e32 v70, 1.0, v72
	v_add_f32_e32 v71, 1.0, v73
	v_rcp_f32_e32 v70, v70
	v_lshlrev_b32_e32 v72, 16, v162
	v_and_b32_e32 v73, 0xffff0000, v162
	v_rcp_f32_e32 v71, v71
	v_mul_f32_e32 v72, 0xbfb8aa3b, v72
	v_mul_f32_e32 v73, 0xbfb8aa3b, v73
	v_exp_f32_e32 v72, v72
	v_exp_f32_e32 v73, v73
	v_pk_mul_f32 v[66:67], v[66:67], v[70:71]
	v_cvt_pk_bf16_f32 v64, v64, v65
	v_cvt_pk_bf16_f32 v65, v66, v67
	v_lshlrev_b32_e32 v66, 16, v163
	v_add_f32_e32 v72, 1.0, v72
	v_add_f32_e32 v73, 1.0, v73
; DI unsigned pk2(float lo, float hi) { f32x2 v = {lo, hi}; bf16x2_t b = __builtin_convertvector(v, bf16x2_t); return __builtin_bit_cast(unsigned, b); }
; DI float lo16(unsigned u) { return __uint_as_float(u << 16); }
; DI float hi16(unsigned u) { return __uint_as_float(u & 0xffff0000u); }
; DI float sigmoidf_(float x) { return __builtin_amdgcn_rcpf(1.f + __expf(-x)); }
;     DI void operator()(const f32x4 (&acc)[2][2][4][2], const Unit& u, int wr, int wc, int fr, int fq) const {
;     ...
; #pragma unroll
;         for (int ai = 0; ai < 2; ++ai)
; #pragma unroll
;             for (int m = 0; m < 4; ++m) { bf16_t* rowp = P + (size_t)(row0 + ai * HALF + m * 16) * LDP + col0;
; #pragma unroll
;                 for (int bj = 0; bj < 2; ++bj) { const f32x4 v0 = acc[ai][bj][m][0], v1 = acc[ai][bj][m][1];
;                     const unsigned gnw[4] = {gn[ai][m][bj].x, gn[ai][m][bj].y, gn[ai][m][bj].z, gn[ai][m][bj].w};
;                     const float o[8] = {v0[0], v0[1], v0[2], v0[3], v1[0], v1[1], v1[2], v1[3]};
;                     u32x4 w;
;                     w.x = pk2(o[0] * sigmoidf_(lo16(gnw[0])), o[1] * sigmoidf_(hi16(gnw[0]))); w.y = pk2(o[2] * sigmoidf_(lo16(gnw[1])), o[3] * sigmoidf_(hi16(gnw[1])));
;                     w.z = pk2(o[4] * sigmoidf_(lo16(gnw[2])), o[5] * sigmoidf_(hi16(gnw[2]))); w.w = pk2(o[6] * sigmoidf_(lo16(gnw[3])), o[7] * sigmoidf_(hi16(gnw[3])));
;                     *(u32x4*)(rowp + bj * HALF) = w; } }
	v_mul_f32_e32 v66, 0xbfb8aa3b, v66
	v_rcp_f32_e32 v72, v72
	v_rcp_f32_e32 v73, v73
	v_exp_f32_e32 v67, v66
	v_and_b32_e32 v66, 0xffff0000, v163
	v_mul_f32_e32 v66, 0xbfb8aa3b, v66
	v_exp_f32_e32 v70, v66
	v_pk_mul_f32 v[60:61], v[60:61], v[72:73]
	v_lshl_add_u64 v[68:69], v[68:69], 0, v[2:3]
	v_cvt_pk_bf16_f32 v66, v60, v61
	v_add_f32_e32 v60, 1.0, v67
	v_lshlrev_b32_e32 v67, 16, v156
	v_add_f32_e32 v61, 1.0, v70
	v_mul_f32_e32 v67, 0xbfb8aa3b, v67
	v_and_b32_e32 v70, 0xffff0000, v156
	v_exp_f32_e32 v67, v67
	v_mul_f32_e32 v70, 0xbfb8aa3b, v70
	v_rcp_f32_e32 v60, v60
	v_exp_f32_e32 v71, v70
	v_rcp_f32_e32 v61, v61
	v_add_f32_e32 v67, 1.0, v67
	v_rcp_f32_e32 v70, v67
	v_add_f32_e32 v67, 1.0, v71
	v_pk_mul_f32 v[60:61], v[62:63], v[60:61]
	v_rcp_f32_e32 v71, v67
	v_cvt_pk_bf16_f32 v67, v60, v61
	v_lshlrev_b32_e32 v60, 16, v157
	v_mul_f32_e32 v60, 0xbfb8aa3b, v60
	v_and_b32_e32 v61, 0xffff0000, v157
	v_exp_f32_e32 v60, v60
	v_mul_f32_e32 v61, 0xbfb8aa3b, v61
	v_exp_f32_e32 v61, v61
	v_pk_mul_f32 v[56:57], v[56:57], v[70:71]
	v_and_b32_e32 v62, 0xffff0000, v158
	v_cvt_pk_bf16_f32 v56, v56, v57
	v_add_f32_e32 v57, 1.0, v60
	v_rcp_f32_e32 v60, v57
	v_add_f32_e32 v57, 1.0, v61
	v_rcp_f32_e32 v61, v57
	v_lshlrev_b32_e32 v57, 16, v158
	v_mul_f32_e32 v57, 0xbfb8aa3b, v57
	v_exp_f32_e32 v57, v57
	v_mul_f32_e32 v62, 0xbfb8aa3b, v62
	v_exp_f32_e32 v62, v62
	v_pk_mul_f32 v[58:59], v[58:59], v[60:61]
	v_lshlrev_b32_e32 v61, 16, v159
	v_add_f32_e32 v57, 1.0, v57
	v_mul_f32_e32 v61, 0xbfb8aa3b, v61
	v_rcp_f32_e32 v60, v57
	v_add_f32_e32 v57, 1.0, v62
	v_exp_f32_e32 v62, v61
	v_and_b32_e32 v61, 0xffff0000, v159
	v_mul_f32_e32 v61, 0xbfb8aa3b, v61
	v_exp_f32_e32 v63, v61
	v_rcp_f32_e32 v61, v57
	v_add_f32_e32 v57, 1.0, v62
	v_rcp_f32_e32 v62, v57
	v_add_f32_e32 v57, 1.0, v63
	v_rcp_f32_e32 v63, v57
	v_pk_mul_f32 v[52:53], v[52:53], v[60:61]
	v_cvt_pk_bf16_f32 v57, v58, v59
	v_cvt_pk_bf16_f32 v58, v52, v53
	v_pk_mul_f32 v[52:53], v[54:55], v[62:63]
	v_lshlrev_b32_e32 v54, 16, v152
	v_and_b32_e32 v55, 0xffff0000, v152
	v_mul_f32_e32 v54, 0xbfb8aa3b, v54
	v_mul_f32_e32 v55, 0xbfb8aa3b, v55
	v_exp_f32_e32 v54, v54
	v_exp_f32_e32 v55, v55
	v_cvt_pk_bf16_f32 v59, v52, v53
	global_store_dwordx4 v[68:69], v[56:59], off offset:256
	v_add_f32_e32 v54, 1.0, v54
	v_add_f32_e32 v55, 1.0, v55
	v_lshlrev_b32_e32 v56, 16, v153
	v_and_b32_e32 v57, 0xffff0000, v153
	v_mul_f32_e32 v56, 0xbfb8aa3b, v56
	v_mul_f32_e32 v57, 0xbfb8aa3b, v57
	v_rcp_f32_e32 v54, v54
	v_rcp_f32_e32 v55, v55
	v_exp_f32_e32 v56, v56
	v_exp_f32_e32 v57, v57
	v_mad_i64_i32 v[52:53], s[0:1], v207, s54, v[204:205]
	v_pk_mul_f32 v[48:49], v[48:49], v[54:55]
	v_add_f32_e32 v54, 1.0, v56
	v_add_f32_e32 v55, 1.0, v57
	v_rcp_f32_e32 v54, v54
	v_lshlrev_b32_e32 v56, 16, v154
	v_and_b32_e32 v57, 0xffff0000, v154
	v_rcp_f32_e32 v55, v55
	v_mul_f32_e32 v56, 0xbfb8aa3b, v56
	v_mul_f32_e32 v57, 0xbfb8aa3b, v57
	v_exp_f32_e32 v56, v56
	v_exp_f32_e32 v57, v57
	v_pk_mul_f32 v[50:51], v[50:51], v[54:55]
	v_cvt_pk_bf16_f32 v48, v48, v49
	v_cvt_pk_bf16_f32 v49, v50, v51
	v_lshlrev_b32_e32 v50, 16, v155
	v_add_f32_e32 v56, 1.0, v56
	v_add_f32_e32 v57, 1.0, v57
	v_mul_f32_e32 v50, 0xbfb8aa3b, v50
	v_rcp_f32_e32 v56, v56
	v_rcp_f32_e32 v57, v57
	v_exp_f32_e32 v51, v50
	v_and_b32_e32 v50, 0xffff0000, v155
	v_mul_f32_e32 v50, 0xbfb8aa3b, v50
	v_exp_f32_e32 v54, v50
	v_pk_mul_f32 v[44:45], v[44:45], v[56:57]
	v_lshl_add_u64 v[52:53], v[52:53], 0, v[2:3]
	v_cvt_pk_bf16_f32 v50, v44, v45
	v_add_f32_e32 v44, 1.0, v51
	v_lshlrev_b32_e32 v51, 16, v148
	v_add_f32_e32 v45, 1.0, v54
	v_mul_f32_e32 v51, 0xbfb8aa3b, v51
	v_and_b32_e32 v54, 0xffff0000, v148
	v_exp_f32_e32 v51, v51
	v_mul_f32_e32 v54, 0xbfb8aa3b, v54
	v_rcp_f32_e32 v44, v44
	v_exp_f32_e32 v55, v54
	v_rcp_f32_e32 v45, v45
	v_add_f32_e32 v51, 1.0, v51
	v_rcp_f32_e32 v54, v51
	v_add_f32_e32 v51, 1.0, v55
	v_pk_mul_f32 v[44:45], v[46:47], v[44:45]
	v_rcp_f32_e32 v55, v51
	v_cvt_pk_bf16_f32 v51, v44, v45
	v_lshlrev_b32_e32 v44, 16, v149
	v_mul_f32_e32 v44, 0xbfb8aa3b, v44
	v_and_b32_e32 v45, 0xffff0000, v149
	v_exp_f32_e32 v44, v44
	v_mul_f32_e32 v45, 0xbfb8aa3b, v45
	v_exp_f32_e32 v45, v45
	v_pk_mul_f32 v[40:41], v[40:41], v[54:55]
	v_and_b32_e32 v46, 0xffff0000, v150
	v_cvt_pk_bf16_f32 v40, v40, v41
	v_add_f32_e32 v41, 1.0, v44
	v_rcp_f32_e32 v44, v41
	v_add_f32_e32 v41, 1.0, v45
	v_rcp_f32_e32 v45, v41
	v_lshlrev_b32_e32 v41, 16, v150
	v_mul_f32_e32 v41, 0xbfb8aa3b, v41
	v_exp_f32_e32 v41, v41
	v_mul_f32_e32 v46, 0xbfb8aa3b, v46
	v_exp_f32_e32 v46, v46
	v_pk_mul_f32 v[42:43], v[42:43], v[44:45]
	v_lshlrev_b32_e32 v45, 16, v151
	v_add_f32_e32 v41, 1.0, v41
	v_mul_f32_e32 v45, 0xbfb8aa3b, v45
	v_rcp_f32_e32 v44, v41
	v_add_f32_e32 v41, 1.0, v46
	v_exp_f32_e32 v46, v45
	v_and_b32_e32 v45, 0xffff0000, v151
	v_mul_f32_e32 v45, 0xbfb8aa3b, v45
	v_exp_f32_e32 v47, v45
	v_rcp_f32_e32 v45, v41
	v_add_f32_e32 v41, 1.0, v46
	v_rcp_f32_e32 v46, v41
	v_add_f32_e32 v41, 1.0, v47
	v_rcp_f32_e32 v47, v41
	v_pk_mul_f32 v[36:37], v[36:37], v[44:45]
	v_cvt_pk_bf16_f32 v41, v42, v43
	v_cvt_pk_bf16_f32 v42, v36, v37
	v_pk_mul_f32 v[36:37], v[38:39], v[46:47]
	v_lshlrev_b32_e32 v38, 16, v144
	v_and_b32_e32 v39, 0xffff0000, v144
	v_mul_f32_e32 v38, 0xbfb8aa3b, v38
	v_mul_f32_e32 v39, 0xbfb8aa3b, v39
	v_exp_f32_e32 v38, v38
	v_exp_f32_e32 v39, v39
	v_cvt_pk_bf16_f32 v43, v36, v37
	global_store_dwordx4 v[52:53], v[40:43], off offset:256
	v_add_f32_e32 v38, 1.0, v38
	v_add_f32_e32 v39, 1.0, v39
	v_lshlrev_b32_e32 v40, 16, v145
	v_and_b32_e32 v41, 0xffff0000, v145
	v_mul_f32_e32 v40, 0xbfb8aa3b, v40
	v_mul_f32_e32 v41, 0xbfb8aa3b, v41
	v_rcp_f32_e32 v38, v38
	v_rcp_f32_e32 v39, v39
	v_exp_f32_e32 v40, v40
; DI unsigned pk2(float lo, float hi) { f32x2 v = {lo, hi}; bf16x2_t b = __builtin_convertvector(v, bf16x2_t); return __builtin_bit_cast(unsigned, b); }
; DI float lo16(unsigned u) { return __uint_as_float(u << 16); }
; DI float hi16(unsigned u) { return __uint_as_float(u & 0xffff0000u); }
; DI float sigmoidf_(float x) { return __builtin_amdgcn_rcpf(1.f + __expf(-x)); }
; template <class Epi>
; DI void gemm_phase(LAS unsigned char* lds, const Gemm g, const StaticOrder& S, const Epi& E) {
;     ...
;         E(acc, cur, wr, wc, fr, fq);
;         if (!has_next) break;
;     DI void operator()(const f32x4 (&acc)[2][2][4][2], const Unit& u, int wr, int wc, int fr, int fq) const {
;     ...
; #pragma unroll
;         for (int ai = 0; ai < 2; ++ai)
; #pragma unroll
;             for (int m = 0; m < 4; ++m) { bf16_t* rowp = P + (size_t)(row0 + ai * HALF + m * 16) * LDP + col0;
; #pragma unroll
;                 for (int bj = 0; bj < 2; ++bj) { const f32x4 v0 = acc[ai][bj][m][0], v1 = acc[ai][bj][m][1];
;                     const unsigned gnw[4] = {gn[ai][m][bj].x, gn[ai][m][bj].y, gn[ai][m][bj].z, gn[ai][m][bj].w};
;                     const float o[8] = {v0[0], v0[1], v0[2], v0[3], v1[0], v1[1], v1[2], v1[3]};
;                     u32x4 w;
;                     w.x = pk2(o[0] * sigmoidf_(lo16(gnw[0])), o[1] * sigmoidf_(hi16(gnw[0]))); w.y = pk2(o[2] * sigmoidf_(lo16(gnw[1])), o[3] * sigmoidf_(hi16(gnw[1])));
;                     w.z = pk2(o[4] * sigmoidf_(lo16(gnw[2])), o[5] * sigmoidf_(hi16(gnw[2]))); w.w = pk2(o[6] * sigmoidf_(lo16(gnw[3])), o[7] * sigmoidf_(hi16(gnw[3])));
;                     *(u32x4*)(rowp + bj * HALF) = w; } }
;     }
	v_exp_f32_e32 v41, v41
	v_mad_i64_i32 v[36:37], s[0:1], v206, s54, v[204:205]
	v_pk_mul_f32 v[32:33], v[32:33], v[38:39]
	v_add_f32_e32 v38, 1.0, v40
	v_add_f32_e32 v39, 1.0, v41
	v_rcp_f32_e32 v38, v38
	v_lshlrev_b32_e32 v40, 16, v146
	v_and_b32_e32 v41, 0xffff0000, v146
	v_rcp_f32_e32 v39, v39
	v_mul_f32_e32 v40, 0xbfb8aa3b, v40
	v_mul_f32_e32 v41, 0xbfb8aa3b, v41
	v_exp_f32_e32 v40, v40
	v_exp_f32_e32 v41, v41
	v_pk_mul_f32 v[34:35], v[34:35], v[38:39]
	v_cvt_pk_bf16_f32 v32, v32, v33
	v_cvt_pk_bf16_f32 v33, v34, v35
	v_lshlrev_b32_e32 v34, 16, v147
	v_add_f32_e32 v40, 1.0, v40
	v_add_f32_e32 v41, 1.0, v41
	v_mul_f32_e32 v34, 0xbfb8aa3b, v34
	v_rcp_f32_e32 v40, v40
	v_rcp_f32_e32 v41, v41
	v_exp_f32_e32 v35, v34
	v_and_b32_e32 v34, 0xffff0000, v147
	v_mul_f32_e32 v34, 0xbfb8aa3b, v34
	v_exp_f32_e32 v38, v34
	v_pk_mul_f32 v[28:29], v[28:29], v[40:41]
	v_lshl_add_u64 v[36:37], v[36:37], 0, v[2:3]
	v_cvt_pk_bf16_f32 v34, v28, v29
	v_add_f32_e32 v28, 1.0, v35
	v_lshlrev_b32_e32 v35, 16, v140
	v_add_f32_e32 v29, 1.0, v38
	v_mul_f32_e32 v35, 0xbfb8aa3b, v35
	v_and_b32_e32 v38, 0xffff0000, v140
	v_exp_f32_e32 v35, v35
	v_mul_f32_e32 v38, 0xbfb8aa3b, v38
	v_rcp_f32_e32 v28, v28
	v_exp_f32_e32 v39, v38
	v_rcp_f32_e32 v29, v29
	v_add_f32_e32 v35, 1.0, v35
	v_rcp_f32_e32 v38, v35
	v_add_f32_e32 v35, 1.0, v39
	v_pk_mul_f32 v[28:29], v[30:31], v[28:29]
	v_rcp_f32_e32 v39, v35
	v_cvt_pk_bf16_f32 v35, v28, v29
	v_lshlrev_b32_e32 v28, 16, v141
	v_mul_f32_e32 v28, 0xbfb8aa3b, v28
	v_and_b32_e32 v29, 0xffff0000, v141
	v_exp_f32_e32 v28, v28
	v_mul_f32_e32 v29, 0xbfb8aa3b, v29
	v_exp_f32_e32 v29, v29
	v_pk_mul_f32 v[24:25], v[24:25], v[38:39]
	v_and_b32_e32 v30, 0xffff0000, v142
	v_cvt_pk_bf16_f32 v24, v24, v25
	v_add_f32_e32 v25, 1.0, v28
	v_rcp_f32_e32 v28, v25
	v_add_f32_e32 v25, 1.0, v29
	v_rcp_f32_e32 v29, v25
	v_lshlrev_b32_e32 v25, 16, v142
	v_mul_f32_e32 v25, 0xbfb8aa3b, v25
	v_exp_f32_e32 v25, v25
	v_mul_f32_e32 v30, 0xbfb8aa3b, v30
	v_exp_f32_e32 v30, v30
	v_pk_mul_f32 v[26:27], v[26:27], v[28:29]
	v_lshlrev_b32_e32 v29, 16, v143
	v_add_f32_e32 v25, 1.0, v25
	v_mul_f32_e32 v29, 0xbfb8aa3b, v29
	v_rcp_f32_e32 v28, v25
	v_add_f32_e32 v25, 1.0, v30
	v_exp_f32_e32 v30, v29
	v_and_b32_e32 v29, 0xffff0000, v143
	v_mul_f32_e32 v29, 0xbfb8aa3b, v29
	v_exp_f32_e32 v31, v29
	v_rcp_f32_e32 v29, v25
	v_add_f32_e32 v25, 1.0, v30
	v_rcp_f32_e32 v30, v25
	v_add_f32_e32 v25, 1.0, v31
	v_rcp_f32_e32 v31, v25
	v_pk_mul_f32 v[20:21], v[20:21], v[28:29]
	v_cvt_pk_bf16_f32 v25, v26, v27
	v_cvt_pk_bf16_f32 v26, v20, v21
	v_pk_mul_f32 v[20:21], v[22:23], v[30:31]
	s_waitcnt vmcnt(0)
	v_and_b32_e32 v22, 0xffff0000, v136
	v_cvt_pk_bf16_f32 v27, v20, v21
	v_mad_i64_i32 v[20:21], s[0:1], v1, s54, v[204:205]
	v_lshlrev_b32_e32 v1, 16, v136
	v_mul_f32_e32 v1, 0xbfb8aa3b, v1
	v_exp_f32_e32 v1, v1
	v_mul_f32_e32 v22, 0xbfb8aa3b, v22
	v_exp_f32_e32 v22, v22
	v_lshl_add_u64 v[20:21], v[20:21], 0, v[2:3]
	v_add_f32_e32 v1, 1.0, v1
	v_rcp_f32_e32 v2, v1
	v_add_f32_e32 v1, 1.0, v22
	v_rcp_f32_e32 v3, v1
	v_lshlrev_b32_e32 v1, 16, v137
	v_mul_f32_e32 v1, 0xbfb8aa3b, v1
	v_and_b32_e32 v22, 0xffff0000, v137
	v_exp_f32_e32 v1, v1
	v_mul_f32_e32 v22, 0xbfb8aa3b, v22
	v_pk_mul_f32 v[2:3], v[16:17], v[2:3]
	v_lshlrev_b32_e32 v16, 16, v138
	v_exp_f32_e32 v23, v22
	v_mul_f32_e32 v16, 0xbfb8aa3b, v16
	v_and_b32_e32 v17, 0xffff0000, v138
	v_exp_f32_e32 v16, v16
	v_mul_f32_e32 v17, 0xbfb8aa3b, v17
	v_exp_f32_e32 v17, v17
	v_add_f32_e32 v1, 1.0, v1
	v_rcp_f32_e32 v22, v1
	v_add_f32_e32 v1, 1.0, v23
	v_rcp_f32_e32 v23, v1
	v_add_f32_e32 v1, 1.0, v16
	global_store_dwordx4 v[36:37], v[24:27], off offset:256
	v_cvt_pk_bf16_f32 v16, v2, v3
	v_pk_mul_f32 v[2:3], v[18:19], v[22:23]
	v_rcp_f32_e32 v24, v1
	v_add_f32_e32 v1, 1.0, v17
	v_rcp_f32_e32 v25, v1
	v_lshlrev_b32_e32 v1, 16, v139
	v_cvt_pk_bf16_f32 v17, v2, v3
	v_mul_f32_e32 v1, 0xbfb8aa3b, v1
	v_pk_mul_f32 v[2:3], v[12:13], v[24:25]
	v_and_b32_e32 v12, 0xffff0000, v139
	v_exp_f32_e32 v1, v1
	v_mul_f32_e32 v12, 0xbfb8aa3b, v12
	v_exp_f32_e32 v12, v12
	v_cvt_pk_bf16_f32 v18, v2, v3
	v_lshlrev_b32_e32 v3, 16, v132
	v_add_f32_e32 v1, 1.0, v1
	v_mul_f32_e32 v3, 0xbfb8aa3b, v3
	v_rcp_f32_e32 v2, v1
	v_add_f32_e32 v1, 1.0, v12
	v_exp_f32_e32 v12, v3
	v_and_b32_e32 v3, 0xffff0000, v132
	v_mul_f32_e32 v3, 0xbfb8aa3b, v3
	v_exp_f32_e32 v13, v3
	v_rcp_f32_e32 v3, v1
	v_add_f32_e32 v1, 1.0, v12
	v_rcp_f32_e32 v12, v1
	v_add_f32_e32 v1, 1.0, v13
	v_rcp_f32_e32 v13, v1
	v_pk_mul_f32 v[2:3], v[14:15], v[2:3]
	v_lshlrev_b32_e32 v1, 16, v133
	v_cvt_pk_bf16_f32 v19, v2, v3
	v_pk_mul_f32 v[2:3], v[8:9], v[12:13]
	v_mul_f32_e32 v1, 0xbfb8aa3b, v1
	v_and_b32_e32 v8, 0xffff0000, v133
	v_exp_f32_e32 v1, v1
	v_mul_f32_e32 v8, 0xbfb8aa3b, v8
	v_exp_f32_e32 v9, v8
	v_cvt_pk_bf16_f32 v2, v2, v3
	v_add_f32_e32 v1, 1.0, v1
	v_rcp_f32_e32 v8, v1
	v_add_f32_e32 v1, 1.0, v9
	v_rcp_f32_e32 v9, v1
	v_lshlrev_b32_e32 v1, 16, v134
	v_mul_f32_e32 v1, 0xbfb8aa3b, v1
	v_and_b32_e32 v3, 0xffff0000, v134
	v_exp_f32_e32 v1, v1
	v_mul_f32_e32 v3, 0xbfb8aa3b, v3
	v_exp_f32_e32 v3, v3
	v_pk_mul_f32 v[8:9], v[10:11], v[8:9]
	v_add_f32_e32 v1, 1.0, v1
	v_rcp_f32_e32 v10, v1
	v_add_f32_e32 v1, 1.0, v3
	v_lshlrev_b32_e32 v3, 16, v135
	v_mul_f32_e32 v3, 0xbfb8aa3b, v3
	v_and_b32_e32 v11, 0xffff0000, v135
	v_exp_f32_e32 v3, v3
	v_mul_f32_e32 v11, 0xbfb8aa3b, v11
	v_exp_f32_e32 v13, v11
	v_rcp_f32_e32 v11, v1
	v_add_f32_e32 v1, 1.0, v3
	v_rcp_f32_e32 v12, v1
	v_add_f32_e32 v1, 1.0, v13
	v_rcp_f32_e32 v13, v1
	v_pk_mul_f32 v[4:5], v[4:5], v[10:11]
	v_cvt_pk_bf16_f32 v3, v8, v9
	v_cvt_pk_bf16_f32 v4, v4, v5
	v_pk_mul_f32 v[6:7], v[6:7], v[12:13]
	global_store_dwordx4 v[228:229], v[128:131], off
	v_cvt_pk_bf16_f32 v5, v6, v7
	global_store_dwordx4 v[116:117], v[112:115], off
	global_store_dwordx4 v[100:101], v[96:99], off
	global_store_dwordx4 v[84:85], v[80:83], off
	global_store_dwordx4 v[68:69], v[64:67], off
	global_store_dwordx4 v[52:53], v[48:51], off
	global_store_dwordx4 v[36:37], v[32:35], off
	global_store_dwordx4 v[20:21], v[16:19], off
	global_store_dwordx4 v[20:21], v[2:5], off offset:256
	s_cmpk_le_u32 s42, 0xff
	s_cbranch_scc1 .Lp4_e1
	s_barrier
.Lp4_e1:
	s_cbranch_vccnz .LBB0_633

; #define PG8_STAGE(bufoff, gbase, voff) do { _Pragma("unroll") for (int _i = 0; _i < 2; ++_i) \
;         __builtin_amdgcn_global_load_lds((const unsigned*)((const char*)(gbase) + (voff)[_i]), (LAS unsigned*)(lds + (bufoff) + ldsw + _i * 8192), 16, 0, 0); } while (0)
; #define PG8_LDA(dst, b, h) do { _Pragma("unroll") for (int m = 0; m < 4; ++m) _Pragma("unroll") for (int k = 0; k < 2; ++k) dst[m][k] = *(const LAS bf16x8*)(lds + PG8_SA(b, h) + aoff + m * 2048 + k * 1024); } while (0)
; #define PG8_LDB(dst, b, h) do { _Pragma("unroll") for (int n = 0; n < 2; ++n) _Pragma("unroll") for (int k = 0; k < 2; ++k) dst[n][k] = *(const LAS bf16x8*)(lds + PG8_SB(b, h) + boff + n * 2048 + k * 1024); } while (0)
; #define PG8_MMA(ai, bj, At, Bt) do { __builtin_amdgcn_s_setprio(1); _Pragma("unroll") for (int m = 0; m < 4; ++m) _Pragma("unroll") for (int n = 0; n < 2; ++n) _Pragma("unroll") for (int k = 0; k < 2; ++k) \
;         acc[ai][bj][m][n] = __builtin_amdgcn_mfma_f32_16x16x32_bf16(Bt[n][k], At[m][k], acc[ai][bj][m][n], 0, 0, 0); __builtin_amdgcn_s_setprio(0); } while (0)
; #define PG8_WAIT_V(n) asm volatile("s_waitcnt vmcnt(" #n ")" ::: "memory")
; template <class Epi>
; DI void gemm_phase(LAS unsigned char* lds, const Gemm g, const StaticOrder& S, const Epi& E) {
;     ...
;         for (int t = 0; t < nt; t += 2) {
;             const bool last = (t == nt - 2);
;             const char* a1 = cA + (size_t)(t + 1) * kstep;
;             const char* a2 = last ? nA : cA + (size_t)(t + 2) * kstep; const char* b2 = last ? nB : cB + (size_t)(t + 2) * kstep;
;             const char* a3 = a2 + kstep; const char* b3 = b2 + kstep;
;             if constexpr (Epi::HAS_MID) { if (t == Epi::MID_T) E.mid(acc, cur, wr, wc, fr, fq); }
;             PG8_LDB(B0, 0, 0); PG8_SCHED; PG8_LDA(At, 0, 0); PG8_STAGE(PG8_SA(1, 1), a1 + hstepA, voffA);
;             PG8_WAIT_L(8); PG8_BAR; PG8_WAIT_L(0); PG8_MMA(0, 0, At, B0); PG8_BAR; PG8_SCHED;
;             PG8_LDB(B1, 0, 1); PG8_STAGE(PG8_SB(0, 0), b2, voffB);
;             PG8_BAR; PG8_WAIT_L(0); PG8_MMA(0, 1, At, B1); PG8_BAR;
;             PG8_LDA(At, 0, 1); PG8_STAGE(PG8_SA(0, 0), a2, voffA);
;             PG8_BAR; PG8_WAIT_L(0); PG8_MMA(1, 0, At, B0); PG8_BAR; PG8_SCHED;
;             PG8_STAGE(PG8_SB(0, 1), b2 + hstepB, voffB);
;             PG8_WAIT_V(6); PG8_BAR; PG8_MMA(1, 1, At, B1); PG8_BAR;
.LBB0_705:
	ds_read_b128 v[144:147], v153
	ds_read_b128 v[156:159], v153 offset:1024
	ds_read_b128 v[160:163], v153 offset:2048
	ds_read_b128 v[164:167], v153 offset:3072
	s_add_u32 s2, s26, 0x100
	s_addc_u32 s3, s27, 0
	s_cmp_eq_u32 s56, 28
	s_cselect_b32 s37, s23, s3
	s_cselect_b32 s36, s22, s2
	s_cselect_b32 s35, s21, s55
	s_cselect_b32 s34, s53, s54
	v_lshl_add_u64 v[148:149], s[26:27], 0, v[136:137]
	s_add_i32 m0, s40, 0xc000
	ds_read_b128 v[168:171], v154
	ds_read_b128 v[172:175], v154 offset:1024
	ds_read_b128 v[176:179], v154 offset:2048
	ds_read_b128 v[180:183], v154 offset:3072
	ds_read_b128 v[184:187], v154 offset:4096
	ds_read_b128 v[188:191], v154 offset:5120
	ds_read_b128 v[192:195], v154 offset:6144
	ds_read_b128 v[196:199], v154 offset:7168
	global_load_lds_dwordx4 v[148:149], off
	v_lshl_add_u64 v[148:149], s[26:27], 0, v[138:139]
	s_add_i32 m0, s40, 0xe000
	s_nop 0
	global_load_lds_dwordx4 v[148:149], off
	s_waitcnt lgkmcnt(8)
	s_barrier
	s_waitcnt lgkmcnt(0)
	s_setprio 1
	s_waitcnt lgkmcnt(0)
	v_mfma_f32_16x16x32_bf16 v[124:127], v[144:147], v[168:171], v[124:127]
	v_mfma_f32_16x16x32_bf16 v[120:123], v[160:163], v[168:171], v[120:123]
	v_mfma_f32_16x16x32_bf16 v[116:119], v[144:147], v[176:179], v[116:119]
	v_mfma_f32_16x16x32_bf16 v[112:115], v[160:163], v[176:179], v[112:115]
	v_mfma_f32_16x16x32_bf16 v[108:111], v[144:147], v[184:187], v[108:111]
	v_mfma_f32_16x16x32_bf16 v[100:103], v[160:163], v[184:187], v[100:103]
	v_mfma_f32_16x16x32_bf16 v[92:95], v[144:147], v[192:195], v[92:95]
	v_mfma_f32_16x16x32_bf16 v[80:83], v[160:163], v[192:195], v[80:83]
	v_mfma_f32_16x16x32_bf16 v[124:127], v[156:159], v[172:175], v[124:127]
	v_mfma_f32_16x16x32_bf16 v[120:123], v[164:167], v[172:175], v[120:123]
	v_mfma_f32_16x16x32_bf16 v[116:119], v[156:159], v[180:183], v[116:119]
	v_mfma_f32_16x16x32_bf16 v[112:115], v[164:167], v[180:183], v[112:115]
	v_mfma_f32_16x16x32_bf16 v[108:111], v[156:159], v[188:191], v[108:111]
	v_mfma_f32_16x16x32_bf16 v[100:103], v[164:167], v[188:191], v[100:103]
	v_mfma_f32_16x16x32_bf16 v[92:95], v[156:159], v[196:199], v[92:95]
	v_mfma_f32_16x16x32_bf16 v[80:83], v[164:167], v[196:199], v[80:83]
	s_setprio 0
	s_barrier
	s_add_i32 s26, s48, s39
	v_lshl_add_u64 v[148:149], s[34:35], 0, v[130:131]
	s_mov_b32 m0, s26
	ds_read_b128 v[200:203], v155
	ds_read_b128 v[204:207], v155 offset:1024
	ds_read_b128 v[208:211], v155 offset:2048
	ds_read_b128 v[212:215], v155 offset:3072
	global_load_lds_dwordx4 v[148:149], off
	v_lshl_add_u64 v[216:217], s[34:35], 0, v[134:135]
	s_add_i32 m0, s26, 0x2000
	s_nop 0
	global_load_lds_dwordx4 v[216:217], off
	s_barrier
	s_waitcnt lgkmcnt(0)
	s_setprio 1
	s_waitcnt lgkmcnt(0)
	v_mfma_f32_16x16x32_bf16 v[104:107], v[200:203], v[168:171], v[104:107]
	v_mfma_f32_16x16x32_bf16 v[96:99], v[208:211], v[168:171], v[96:99]
	v_mfma_f32_16x16x32_bf16 v[88:91], v[200:203], v[176:179], v[88:91]
	v_mfma_f32_16x16x32_bf16 v[84:87], v[208:211], v[176:179], v[84:87]
	v_mfma_f32_16x16x32_bf16 v[76:79], v[200:203], v[184:187], v[76:79]
	v_mfma_f32_16x16x32_bf16 v[72:75], v[208:211], v[184:187], v[72:75]
	v_mfma_f32_16x16x32_bf16 v[68:71], v[200:203], v[192:195], v[68:71]
	v_mfma_f32_16x16x32_bf16 v[64:67], v[208:211], v[192:195], v[64:67]
	v_mfma_f32_16x16x32_bf16 v[104:107], v[204:207], v[172:175], v[104:107]
	v_mfma_f32_16x16x32_bf16 v[96:99], v[212:215], v[172:175], v[96:99]
	v_mfma_f32_16x16x32_bf16 v[88:91], v[204:207], v[180:183], v[88:91]
	v_mfma_f32_16x16x32_bf16 v[84:87], v[212:215], v[180:183], v[84:87]
	v_mfma_f32_16x16x32_bf16 v[76:79], v[204:207], v[188:191], v[76:79]
	v_mfma_f32_16x16x32_bf16 v[72:75], v[212:215], v[188:191], v[72:75]
	v_mfma_f32_16x16x32_bf16 v[68:71], v[204:207], v[196:199], v[68:71]
	v_mfma_f32_16x16x32_bf16 v[64:67], v[212:215], v[196:199], v[64:67]
	s_setprio 0
	s_mov_b32 m0, s40
	v_lshl_add_u64 v[218:219], s[36:37], 0, v[128:129]
	s_barrier
	ds_read_b128 v[168:171], v154 offset:16384
	ds_read_b128 v[172:175], v154 offset:17408
	ds_read_b128 v[176:179], v154 offset:18432
	ds_read_b128 v[180:183], v154 offset:19456
	ds_read_b128 v[184:187], v154 offset:20480
	ds_read_b128 v[188:191], v154 offset:21504
	ds_read_b128 v[192:195], v154 offset:22528
	ds_read_b128 v[196:199], v154 offset:23552
	global_load_lds_dwordx4 v[218:219], off
	v_lshl_add_u64 v[220:221], s[36:37], 0, v[132:133]
	s_mov_b32 m0, s41
	s_nop 0
	global_load_lds_dwordx4 v[220:221], off
	s_barrier
	s_waitcnt lgkmcnt(0)
	s_setprio 1
	s_waitcnt lgkmcnt(0)
	v_mfma_f32_16x16x32_bf16 v[60:63], v[144:147], v[168:171], v[60:63]
	v_mfma_f32_16x16x32_bf16 v[56:59], v[160:163], v[168:171], v[56:59]
	v_mfma_f32_16x16x32_bf16 v[52:55], v[144:147], v[176:179], v[52:55]
	v_mfma_f32_16x16x32_bf16 v[48:51], v[160:163], v[176:179], v[48:51]
	v_mfma_f32_16x16x32_bf16 v[44:47], v[144:147], v[184:187], v[44:47]
	v_mfma_f32_16x16x32_bf16 v[36:39], v[160:163], v[184:187], v[36:39]
	v_mfma_f32_16x16x32_bf16 v[28:31], v[144:147], v[192:195], v[28:31]
	v_mfma_f32_16x16x32_bf16 v[16:19], v[160:163], v[192:195], v[16:19]
	v_mfma_f32_16x16x32_bf16 v[60:63], v[156:159], v[172:175], v[60:63]
	v_mfma_f32_16x16x32_bf16 v[56:59], v[164:167], v[172:175], v[56:59]
	v_mfma_f32_16x16x32_bf16 v[52:55], v[156:159], v[180:183], v[52:55]
	v_mfma_f32_16x16x32_bf16 v[48:51], v[164:167], v[180:183], v[48:51]
	v_mfma_f32_16x16x32_bf16 v[44:47], v[156:159], v[188:191], v[44:47]
	v_mfma_f32_16x16x32_bf16 v[36:39], v[164:167], v[188:191], v[36:39]
	v_mfma_f32_16x16x32_bf16 v[28:31], v[156:159], v[196:199], v[28:31]
	v_mfma_f32_16x16x32_bf16 v[16:19], v[164:167], v[196:199], v[16:19]
	s_setprio 0
	s_barrier
; #define PG8_STAGE(bufoff, gbase, voff) do { _Pragma("unroll") for (int _i = 0; _i < 2; ++_i) \
;         __builtin_amdgcn_global_load_lds((const unsigned*)((const char*)(gbase) + (voff)[_i]), (LAS unsigned*)(lds + (bufoff) + ldsw + _i * 8192), 16, 0, 0); } while (0)
; #define PG8_LDA(dst, b, h) do { _Pragma("unroll") for (int m = 0; m < 4; ++m) _Pragma("unroll") for (int k = 0; k < 2; ++k) dst[m][k] = *(const LAS bf16x8*)(lds + PG8_SA(b, h) + aoff + m * 2048 + k * 1024); } while (0)
; #define PG8_LDB(dst, b, h) do { _Pragma("unroll") for (int n = 0; n < 2; ++n) _Pragma("unroll") for (int k = 0; k < 2; ++k) dst[n][k] = *(const LAS bf16x8*)(lds + PG8_SB(b, h) + boff + n * 2048 + k * 1024); } while (0)
; #define PG8_MMA(ai, bj, At, Bt) do { __builtin_amdgcn_s_setprio(1); _Pragma("unroll") for (int m = 0; m < 4; ++m) _Pragma("unroll") for (int n = 0; n < 2; ++n) _Pragma("unroll") for (int k = 0; k < 2; ++k) \
;         acc[ai][bj][m][n] = __builtin_amdgcn_mfma_f32_16x16x32_bf16(Bt[n][k], At[m][k], acc[ai][bj][m][n], 0, 0, 0); __builtin_amdgcn_s_setprio(0); } while (0)
; #define PG8_WAIT_V(n) asm volatile("s_waitcnt vmcnt(" #n ")" ::: "memory")
; #define PG8_WAIT_L(n) asm volatile("s_waitcnt lgkmcnt(" #n ")" ::: "memory")
; #define PG8_BAR __builtin_amdgcn_s_barrier()
; #define PG8_SCHED __builtin_amdgcn_sched_barrier(0)
; template <class Epi>
; DI void gemm_phase(LAS unsigned char* lds, const Gemm g, const StaticOrder& S, const Epi& E) {
;     ...
;             PG8_WAIT_V(6); PG8_BAR; PG8_MMA(1, 1, At, B1); PG8_BAR;
;             PG8_LDB(B0, 1, 0); PG8_SCHED; PG8_LDA(At, 1, 0); PG8_STAGE(PG8_SA(0, 1), a2 + hstepA, voffA);
;             PG8_WAIT_L(8); PG8_BAR; PG8_WAIT_L(0); PG8_MMA(0, 0, At, B0); PG8_BAR; PG8_SCHED;
;             PG8_LDB(B1, 1, 1); PG8_STAGE(PG8_SB(1, 0), b3, voffB);
;             PG8_BAR; PG8_WAIT_L(0); PG8_MMA(0, 1, At, B1); PG8_BAR;
;             PG8_LDA(At, 1, 1); PG8_STAGE(PG8_SA(1, 0), a3, voffA);
;             PG8_BAR; PG8_WAIT_L(0); PG8_MMA(1, 0, At, B0); PG8_BAR; PG8_SCHED;
	s_add_u32 s26, s34, 0x80000
	s_addc_u32 s27, s35, 0
	s_add_i32 s57, s49, s39
	v_lshl_add_u64 v[144:145], s[26:27], 0, v[130:131]
	s_mov_b32 m0, s57
	s_nop 0
	global_load_lds_dwordx4 v[144:145], off
	v_lshl_add_u64 v[144:145], s[26:27], 0, v[134:135]
	s_add_i32 m0, s57, 0x2000
	s_nop 0
	global_load_lds_dwordx4 v[144:145], off
	s_waitcnt vmcnt(6)
	s_barrier
	s_setprio 1
	v_mfma_f32_16x16x32_bf16 v[40:43], v[200:203], v[168:171], v[40:43]
	v_mfma_f32_16x16x32_bf16 v[32:35], v[208:211], v[168:171], v[32:35]
	v_mfma_f32_16x16x32_bf16 v[24:27], v[200:203], v[176:179], v[24:27]
	v_mfma_f32_16x16x32_bf16 v[20:23], v[208:211], v[176:179], v[20:23]
	v_mfma_f32_16x16x32_bf16 v[12:15], v[200:203], v[184:187], v[12:15]
	v_mfma_f32_16x16x32_bf16 v[8:11], v[208:211], v[184:187], v[8:11]
	v_mfma_f32_16x16x32_bf16 v[4:7], v[200:203], v[192:195], v[4:7]
	v_mfma_f32_16x16x32_bf16 v[0:3], v[208:211], v[192:195], v[0:3]
	v_mfma_f32_16x16x32_bf16 v[40:43], v[204:207], v[172:175], v[40:43]
	v_mfma_f32_16x16x32_bf16 v[32:35], v[212:215], v[172:175], v[32:35]
	v_mfma_f32_16x16x32_bf16 v[24:27], v[204:207], v[180:183], v[24:27]
	v_mfma_f32_16x16x32_bf16 v[20:23], v[212:215], v[180:183], v[20:23]
	v_mfma_f32_16x16x32_bf16 v[12:15], v[204:207], v[188:191], v[12:15]
	v_mfma_f32_16x16x32_bf16 v[8:11], v[212:215], v[188:191], v[8:11]
	v_mfma_f32_16x16x32_bf16 v[4:7], v[204:207], v[196:199], v[4:7]
	v_mfma_f32_16x16x32_bf16 v[0:3], v[212:215], v[196:199], v[0:3]
	s_setprio 0
	s_add_i32 s57, 0, 0x18000
	v_add_u32_e32 v164, s57, v151
	s_barrier
	ds_read_b128 v[144:147], v164
	ds_read_b128 v[156:159], v164 offset:1024
	ds_read_b128 v[160:163], v164 offset:2048
	ds_read_b128 v[164:167], v164 offset:3072
	s_add_u32 s26, s36, 0x3b0000
	s_addc_u32 s27, s37, 0
	s_mov_b32 m0, s42
	v_lshl_add_u64 v[200:201], s[26:27], 0, v[128:129]
	ds_read_b128 v[168:171], v154 offset:32768
	ds_read_b128 v[172:175], v154 offset:33792
	ds_read_b128 v[176:179], v154 offset:34816
	ds_read_b128 v[180:183], v154 offset:35840
	ds_read_b128 v[184:187], v154 offset:36864
	ds_read_b128 v[188:191], v154 offset:37888
	ds_read_b128 v[192:195], v154 offset:38912
	ds_read_b128 v[196:199], v154 offset:39936
	global_load_lds_dwordx4 v[200:201], off
	v_lshl_add_u64 v[200:201], s[26:27], 0, v[132:133]
	s_mov_b32 m0, s43
	s_nop 0
	global_load_lds_dwordx4 v[200:201], off
	s_waitcnt lgkmcnt(8)
	s_barrier
	s_waitcnt lgkmcnt(0)
	s_setprio 1
	s_waitcnt lgkmcnt(0)
	v_mfma_f32_16x16x32_bf16 v[124:127], v[144:147], v[168:171], v[124:127]
	v_mfma_f32_16x16x32_bf16 v[120:123], v[160:163], v[168:171], v[120:123]
	v_mfma_f32_16x16x32_bf16 v[116:119], v[144:147], v[176:179], v[116:119]
	v_mfma_f32_16x16x32_bf16 v[112:115], v[160:163], v[176:179], v[112:115]
	v_mfma_f32_16x16x32_bf16 v[108:111], v[144:147], v[184:187], v[108:111]
	v_mfma_f32_16x16x32_bf16 v[100:103], v[160:163], v[184:187], v[100:103]
	v_mfma_f32_16x16x32_bf16 v[92:95], v[144:147], v[192:195], v[92:95]
	v_mfma_f32_16x16x32_bf16 v[80:83], v[160:163], v[192:195], v[80:83]
	v_mfma_f32_16x16x32_bf16 v[124:127], v[156:159], v[172:175], v[124:127]
	v_mfma_f32_16x16x32_bf16 v[120:123], v[164:167], v[172:175], v[120:123]
	v_mfma_f32_16x16x32_bf16 v[116:119], v[156:159], v[180:183], v[116:119]
	v_mfma_f32_16x16x32_bf16 v[112:115], v[164:167], v[180:183], v[112:115]
	v_mfma_f32_16x16x32_bf16 v[108:111], v[156:159], v[188:191], v[108:111]
	v_mfma_f32_16x16x32_bf16 v[100:103], v[164:167], v[188:191], v[100:103]
	v_mfma_f32_16x16x32_bf16 v[92:95], v[156:159], v[196:199], v[92:95]
	v_mfma_f32_16x16x32_bf16 v[80:83], v[164:167], v[196:199], v[80:83]
	s_setprio 0
	s_barrier
	s_add_i32 s36, 0, 0x1c000
	s_add_i32 s26, s57, s39
	v_add_u32_e32 v212, s36, v151
	v_lshl_add_u64 v[148:149], v[148:149], 0, s[4:5]
	s_mov_b32 m0, s26
	ds_read_b128 v[200:203], v212
	ds_read_b128 v[204:207], v212 offset:1024
	ds_read_b128 v[208:211], v212 offset:2048
	ds_read_b128 v[212:215], v212 offset:3072
	global_load_lds_dwordx4 v[148:149], off
	v_lshl_add_u64 v[148:149], v[216:217], 0, s[4:5]
	s_add_i32 m0, s26, 0x2000
	s_nop 0
	global_load_lds_dwordx4 v[148:149], off
	s_barrier
	s_waitcnt lgkmcnt(0)
	s_setprio 1
	s_waitcnt lgkmcnt(0)
	v_mfma_f32_16x16x32_bf16 v[104:107], v[200:203], v[168:171], v[104:107]
	v_mfma_f32_16x16x32_bf16 v[96:99], v[208:211], v[168:171], v[96:99]
	v_mfma_f32_16x16x32_bf16 v[88:91], v[200:203], v[176:179], v[88:91]
	v_mfma_f32_16x16x32_bf16 v[84:87], v[208:211], v[176:179], v[84:87]
	v_mfma_f32_16x16x32_bf16 v[76:79], v[200:203], v[184:187], v[76:79]
	v_mfma_f32_16x16x32_bf16 v[72:75], v[208:211], v[184:187], v[72:75]
	v_mfma_f32_16x16x32_bf16 v[68:71], v[200:203], v[192:195], v[68:71]
	v_mfma_f32_16x16x32_bf16 v[64:67], v[208:211], v[192:195], v[64:67]
	v_mfma_f32_16x16x32_bf16 v[104:107], v[204:207], v[172:175], v[104:107]
	v_mfma_f32_16x16x32_bf16 v[96:99], v[212:215], v[172:175], v[96:99]
	v_mfma_f32_16x16x32_bf16 v[88:91], v[204:207], v[180:183], v[88:91]
	v_mfma_f32_16x16x32_bf16 v[84:87], v[212:215], v[180:183], v[84:87]
	v_mfma_f32_16x16x32_bf16 v[76:79], v[204:207], v[188:191], v[76:79]
	v_mfma_f32_16x16x32_bf16 v[72:75], v[212:215], v[188:191], v[72:75]
	v_mfma_f32_16x16x32_bf16 v[68:71], v[204:207], v[196:199], v[68:71]
	v_mfma_f32_16x16x32_bf16 v[64:67], v[212:215], v[196:199], v[64:67]
	s_setprio 0
	s_mov_b32 m0, s45
	v_lshl_add_u64 v[148:149], v[218:219], 0, s[4:5]
	s_barrier
	ds_read_b128 v[168:171], v154 offset:49152
	ds_read_b128 v[172:175], v154 offset:50176
	ds_read_b128 v[176:179], v154 offset:51200
	ds_read_b128 v[180:183], v154 offset:52224
	ds_read_b128 v[184:187], v154 offset:53248
	ds_read_b128 v[188:191], v154 offset:54272
	ds_read_b128 v[192:195], v154 offset:55296
	ds_read_b128 v[196:199], v154 offset:56320
	global_load_lds_dwordx4 v[148:149], off
	v_lshl_add_u64 v[148:149], v[220:221], 0, s[4:5]
	s_mov_b32 m0, s46
	s_nop 0
	global_load_lds_dwordx4 v[148:149], off
	s_barrier
; #define PG8_STAGE(bufoff, gbase, voff) do { _Pragma("unroll") for (int _i = 0; _i < 2; ++_i) \
;         __builtin_amdgcn_global_load_lds((const unsigned*)((const char*)(gbase) + (voff)[_i]), (LAS unsigned*)(lds + (bufoff) + ldsw + _i * 8192), 16, 0, 0); } while (0)
; #define PG8_MMA(ai, bj, At, Bt) do { __builtin_amdgcn_s_setprio(1); _Pragma("unroll") for (int m = 0; m < 4; ++m) _Pragma("unroll") for (int n = 0; n < 2; ++n) _Pragma("unroll") for (int k = 0; k < 2; ++k) \
;         acc[ai][bj][m][n] = __builtin_amdgcn_mfma_f32_16x16x32_bf16(Bt[n][k], At[m][k], acc[ai][bj][m][n], 0, 0, 0); __builtin_amdgcn_s_setprio(0); } while (0)
; #define PG8_WAIT_V(n) asm volatile("s_waitcnt vmcnt(" #n ")" ::: "memory")
; #define PG8_WAIT_L(n) asm volatile("s_waitcnt lgkmcnt(" #n ")" ::: "memory")
; #define PG8_BAR __builtin_amdgcn_s_barrier()
; #define PG8_SCHED __builtin_amdgcn_sched_barrier(0)
; template <class Epi>
; DI void gemm_phase(LAS unsigned char* lds, const Gemm g, const StaticOrder& S, const Epi& E) {
;     ...
;             PG8_BAR; PG8_WAIT_L(0); PG8_MMA(1, 0, At, B0); PG8_BAR; PG8_SCHED;
;             PG8_STAGE(PG8_SB(1, 1), b3 + hstepB, voffB);
;             PG8_WAIT_V(6); PG8_BAR; PG8_MMA(1, 1, At, B1); PG8_BAR;
;         }
;         E(acc, cur, wr, wc, fr, fq);
;     DI void operator()(const f32x4 (&acc)[2][2][4][2], const Unit& u, int wr, int wc, int fr, int fq) const {
;         const int row0 = u.pm * BM + wr * 64 + fr, col0 = u.pn * BM + wc * 32 + 4 * fq;
; #pragma unroll
;         for (int ai = 0; ai < 2; ++ai) {
;             f32x4 xv[4][2][2];
; #pragma unroll
;             for (int m = 0; m < 4; ++m) { const size_t off = (size_t)(row0 + ai * HALF + m * 16) * DM + col0;
; #pragma unroll
;                 for (int bj = 0; bj < 2; ++bj)
; #pragma unroll
;                     for (int n = 0; n < 2; ++n) xv[m][bj][n] = *(const f32x4*)(X + off + bj * HALF + n * 16); }
	s_waitcnt lgkmcnt(0)
	s_setprio 1
	s_waitcnt lgkmcnt(0)
	v_mfma_f32_16x16x32_bf16 v[60:63], v[144:147], v[168:171], v[60:63]
	v_mfma_f32_16x16x32_bf16 v[56:59], v[160:163], v[168:171], v[56:59]
	v_mfma_f32_16x16x32_bf16 v[52:55], v[144:147], v[176:179], v[52:55]
	v_mfma_f32_16x16x32_bf16 v[48:51], v[160:163], v[176:179], v[48:51]
	v_mfma_f32_16x16x32_bf16 v[44:47], v[144:147], v[184:187], v[44:47]
	v_mfma_f32_16x16x32_bf16 v[36:39], v[160:163], v[184:187], v[36:39]
	v_mfma_f32_16x16x32_bf16 v[28:31], v[144:147], v[192:195], v[28:31]
	v_mfma_f32_16x16x32_bf16 v[16:19], v[160:163], v[192:195], v[16:19]
	v_mfma_f32_16x16x32_bf16 v[60:63], v[156:159], v[172:175], v[60:63]
	v_mfma_f32_16x16x32_bf16 v[56:59], v[164:167], v[172:175], v[56:59]
	v_mfma_f32_16x16x32_bf16 v[52:55], v[156:159], v[180:183], v[52:55]
	v_mfma_f32_16x16x32_bf16 v[48:51], v[164:167], v[180:183], v[48:51]
	v_mfma_f32_16x16x32_bf16 v[44:47], v[156:159], v[188:191], v[44:47]
	v_mfma_f32_16x16x32_bf16 v[36:39], v[164:167], v[188:191], v[36:39]
	v_mfma_f32_16x16x32_bf16 v[28:31], v[156:159], v[196:199], v[28:31]
	v_mfma_f32_16x16x32_bf16 v[16:19], v[164:167], v[196:199], v[16:19]
	s_setprio 0
	s_barrier
	s_add_u32 s26, s34, 0x80080
	s_addc_u32 s27, s35, 0
	s_add_i32 s34, s36, s39
	v_lshl_add_u64 v[144:145], s[26:27], 0, v[130:131]
	s_mov_b32 m0, s34
	s_nop 0
	global_load_lds_dwordx4 v[144:145], off
	v_lshl_add_u64 v[144:145], s[26:27], 0, v[134:135]
	s_add_i32 m0, s34, 0x2000
	s_nop 0
	global_load_lds_dwordx4 v[144:145], off
	s_waitcnt vmcnt(6)
	s_barrier
	s_setprio 1
	v_mfma_f32_16x16x32_bf16 v[40:43], v[200:203], v[168:171], v[40:43]
	v_mfma_f32_16x16x32_bf16 v[32:35], v[208:211], v[168:171], v[32:35]
	v_mfma_f32_16x16x32_bf16 v[24:27], v[200:203], v[176:179], v[24:27]
	v_mfma_f32_16x16x32_bf16 v[20:23], v[208:211], v[176:179], v[20:23]
	v_mfma_f32_16x16x32_bf16 v[12:15], v[200:203], v[184:187], v[12:15]
	v_mfma_f32_16x16x32_bf16 v[8:11], v[208:211], v[184:187], v[8:11]
	v_mfma_f32_16x16x32_bf16 v[4:7], v[200:203], v[192:195], v[4:7]
	v_mfma_f32_16x16x32_bf16 v[0:3], v[208:211], v[192:195], v[0:3]
	v_mfma_f32_16x16x32_bf16 v[40:43], v[204:207], v[172:175], v[40:43]
	v_mfma_f32_16x16x32_bf16 v[32:35], v[212:215], v[172:175], v[32:35]
	v_mfma_f32_16x16x32_bf16 v[24:27], v[204:207], v[180:183], v[24:27]
	v_mfma_f32_16x16x32_bf16 v[20:23], v[212:215], v[180:183], v[20:23]
	v_mfma_f32_16x16x32_bf16 v[12:15], v[204:207], v[188:191], v[12:15]
	v_mfma_f32_16x16x32_bf16 v[8:11], v[212:215], v[188:191], v[8:11]
	v_mfma_f32_16x16x32_bf16 v[4:7], v[204:207], v[196:199], v[4:7]
	v_mfma_f32_16x16x32_bf16 v[0:3], v[212:215], v[196:199], v[0:3]
	s_setprio 0
	s_add_i32 s56, s56, 2
	s_add_u32 s54, s54, 0x100
	s_addc_u32 s55, s55, 0
	s_cmp_gt_u32 s56, 29
	s_mov_b64 s[26:27], s[2:3]
	s_barrier
	s_cbranch_scc0 .LBB0_705
	s_cmpk_gt_u32 s7, 0xff
	s_cbranch_scc1 .Lp5_e0
	s_barrier
.Lp5_e0:
	v_lshl_add_u32 v204, s51, 8, v150
	v_lshl_or_b32 v144, s52, 8, v152
	v_ashrrev_i32_e32 v205, 31, v204
	v_ashrrev_i32_e32 v145, 31, v144
	v_lshlrev_b64 v[148:149], 13, v[204:205]
	v_or_b32_e32 v172, 16, v204
	v_or_b32_e32 v188, 32, v204
	v_or_b32_e32 v204, 48, v204
	v_lshlrev_b64 v[144:145], 2, v[144:145]
	v_ashrrev_i32_e32 v173, 31, v172
	v_ashrrev_i32_e32 v189, 31, v188
	v_ashrrev_i32_e32 v205, 31, v204
	v_lshl_add_u64 v[146:147], s[12:13], 0, v[144:145]
	v_lshlrev_b64 v[220:221], 13, v[172:173]
	v_lshlrev_b64 v[222:223], 13, v[188:189]
	v_lshlrev_b64 v[224:225], 13, v[204:205]
	v_lshl_add_u64 v[168:169], v[146:147], 0, v[148:149]
	v_lshl_add_u64 v[184:185], v[146:147], 0, v[220:221]
	v_lshl_add_u64 v[200:201], v[146:147], 0, v[222:223]
	v_lshl_add_u64 v[216:217], v[146:147], 0, v[224:225]
	global_load_dwordx4 v[156:159], v[168:169], off
	global_load_dwordx4 v[160:163], v[168:169], off offset:64
	global_load_dwordx4 v[164:167], v[168:169], off offset:512
	s_nop 0
	global_load_dwordx4 v[168:171], v[168:169], off offset:576
	s_nop 0
	global_load_dwordx4 v[172:175], v[184:185], off
	global_load_dwordx4 v[176:179], v[184:185], off offset:64
	global_load_dwordx4 v[180:183], v[184:185], off offset:512
	s_nop 0
	global_load_dwordx4 v[184:187], v[184:185], off offset:576
	s_nop 0
	global_load_dwordx4 v[188:191], v[200:201], off
	global_load_dwordx4 v[192:195], v[200:201], off offset:64
	global_load_dwordx4 v[196:199], v[200:201], off offset:512
	s_nop 0
	global_load_dwordx4 v[200:203], v[200:201], off offset:576
	s_nop 0
	global_load_dwordx4 v[204:207], v[216:217], off
	global_load_dwordx4 v[208:211], v[216:217], off offset:64
	global_load_dwordx4 v[212:215], v[216:217], off offset:512
	s_nop 0
	global_load_dwordx4 v[216:219], v[216:217], off offset:576
	v_lshl_add_u64 v[226:227], s[28:29], 0, v[148:149]
	v_lshl_add_u64 v[224:225], s[28:29], 0, v[224:225]
	v_lshl_add_u64 v[226:227], v[226:227], 0, v[144:145]
	v_lshl_add_u64 v[220:221], s[28:29], 0, v[220:221]
	v_lshl_add_u64 v[222:223], s[28:29], 0, v[222:223]
	v_lshl_add_u64 v[224:225], v[224:225], 0, v[144:145]
	v_lshl_add_u64 v[220:221], v[220:221], 0, v[144:145]
	v_lshl_add_u64 v[222:223], v[222:223], 0, v[144:145]
	s_and_b64 vcc, exec, s[0:1]
	s_mov_b32 s52, s20
	s_mov_b32 s51, s50
	s_mov_b64 s[34:35], s[24:25]
	s_mov_b64 s[26:27], s[22:23]
	s_waitcnt vmcnt(0)
; #define PG8_WAIT_V(n) asm volatile("s_waitcnt vmcnt(" #n ")" ::: "memory")
; #define PG8_BAR __builtin_amdgcn_s_barrier()
; template <class Epi>
; DI void gemm_phase(LAS unsigned char* lds, const Gemm g, const StaticOrder& S, const Epi& E) {
;     ...
;         E(acc, cur, wr, wc, fr, fq);
;         if (!has_next) break;
; #pragma unroll
;         for (int a = 0; a < 2; ++a)
; #pragma unroll
;             for (int b = 0; b < 2; ++b)
; #pragma unroll
;                 for (int m = 0; m < 4; ++m)
; #pragma unroll
;                     for (int n = 0; n < 2; ++n) acc[a][b][m][n] = (f32x4){0.f, 0.f, 0.f, 0.f};
;         cur = nxt; cA = nA; cB = nB; ++ui;
;     }
;     PG8_WAIT_V(0);
;     if (wr == 0) PG8_BAR;
;     DI void operator()(const f32x4 (&acc)[2][2][4][2], const Unit& u, int wr, int wc, int fr, int fq) const {
;     ...
;             for (int m = 0; m < 4; ++m) { const size_t off = (size_t)(row0 + ai * HALF + m * 16) * DM + col0;
; #pragma unroll
;                 for (int bj = 0; bj < 2; ++bj)
; #pragma unroll
;                     for (int n = 0; n < 2; ++n) xv[m][bj][n] = *(const f32x4*)(X + off + bj * HALF + n * 16); }
; #pragma unroll
;             for (int m = 0; m < 4; ++m) { const size_t off = (size_t)(row0 + ai * HALF + m * 16) * DM + col0;
; #pragma unroll
;                 for (int bj = 0; bj < 2; ++bj)
; #pragma unroll
;                     for (int n = 0; n < 2; ++n) *(f32x4*)(C + off + bj * HALF + n * 16) = acc[ai][bj][m][n] + xv[m][bj][n]; }
;             asm volatile("" ::: "memory");
;         }
	v_pk_add_f32 v[126:127], v[126:127], v[158:159]
	v_pk_add_f32 v[124:125], v[124:125], v[156:157]
	v_pk_add_f32 v[122:123], v[122:123], v[162:163]
	v_pk_add_f32 v[120:121], v[120:121], v[160:161]
	v_pk_add_f32 v[106:107], v[106:107], v[166:167]
	v_pk_add_f32 v[70:71], v[70:71], v[214:215]
	v_pk_add_f32 v[68:69], v[68:69], v[212:213]
	v_pk_add_f32 v[66:67], v[66:67], v[218:219]
	v_pk_add_f32 v[64:65], v[64:65], v[216:217]
	v_pk_add_f32 v[104:105], v[104:105], v[164:165]
	v_pk_add_f32 v[98:99], v[98:99], v[170:171]
	v_pk_add_f32 v[96:97], v[96:97], v[168:169]
	v_pk_add_f32 v[118:119], v[118:119], v[174:175]
	v_pk_add_f32 v[116:117], v[116:117], v[172:173]
	v_pk_add_f32 v[114:115], v[114:115], v[178:179]
	v_pk_add_f32 v[112:113], v[112:113], v[176:177]
	v_pk_add_f32 v[90:91], v[90:91], v[182:183]
	v_pk_add_f32 v[88:89], v[88:89], v[180:181]
	v_pk_add_f32 v[86:87], v[86:87], v[186:187]
	v_pk_add_f32 v[84:85], v[84:85], v[184:185]
	v_pk_add_f32 v[110:111], v[110:111], v[190:191]
	v_pk_add_f32 v[108:109], v[108:109], v[188:189]
	v_pk_add_f32 v[102:103], v[102:103], v[194:195]
	v_pk_add_f32 v[100:101], v[100:101], v[192:193]
	v_pk_add_f32 v[78:79], v[78:79], v[198:199]
	v_pk_add_f32 v[76:77], v[76:77], v[196:197]
	v_pk_add_f32 v[74:75], v[74:75], v[202:203]
	v_pk_add_f32 v[72:73], v[72:73], v[200:201]
	v_pk_add_f32 v[94:95], v[94:95], v[206:207]
	v_pk_add_f32 v[92:93], v[92:93], v[204:205]
	v_pk_add_f32 v[82:83], v[82:83], v[210:211]
	v_pk_add_f32 v[80:81], v[80:81], v[208:209]
	global_store_dwordx4 v[226:227], v[124:127], off
	global_store_dwordx4 v[226:227], v[120:123], off offset:64
	global_store_dwordx4 v[226:227], v[104:107], off offset:512
	global_store_dwordx4 v[226:227], v[96:99], off offset:576
	global_store_dwordx4 v[220:221], v[116:119], off
	global_store_dwordx4 v[220:221], v[112:115], off offset:64
	global_store_dwordx4 v[220:221], v[88:91], off offset:512
	global_store_dwordx4 v[220:221], v[84:87], off offset:576
	global_store_dwordx4 v[222:223], v[108:111], off
	global_store_dwordx4 v[222:223], v[100:103], off offset:64
	global_store_dwordx4 v[222:223], v[76:79], off offset:512
	global_store_dwordx4 v[222:223], v[72:75], off offset:576
	global_store_dwordx4 v[224:225], v[92:95], off
	global_store_dwordx4 v[224:225], v[80:83], off offset:64
	global_store_dwordx4 v[224:225], v[68:71], off offset:512
	global_store_dwordx4 v[224:225], v[64:67], off offset:576
	v_lshl_add_u64 v[156:157], v[148:149], 0, s[8:9]
	v_lshl_add_u64 v[158:159], v[148:149], 0, s[14:15]
	v_lshl_add_u64 v[160:161], v[148:149], 0, s[16:17]
	v_lshl_add_u64 v[148:149], v[148:149], 0, s[18:19]
	v_lshl_add_u64 v[80:81], v[146:147], 0, v[156:157]
	v_lshl_add_u64 v[92:93], v[146:147], 0, v[158:159]
	v_lshl_add_u64 v[108:109], v[146:147], 0, v[160:161]
	v_lshl_add_u64 v[124:125], v[146:147], 0, v[148:149]
	global_load_dwordx4 v[64:67], v[80:81], off
	global_load_dwordx4 v[68:71], v[80:81], off offset:64
	global_load_dwordx4 v[72:75], v[80:81], off offset:512
	global_load_dwordx4 v[76:79], v[80:81], off offset:576
	s_nop 0
	global_load_dwordx4 v[80:83], v[92:93], off
	global_load_dwordx4 v[84:87], v[92:93], off offset:64
	global_load_dwordx4 v[88:91], v[92:93], off offset:512
	s_nop 0
	global_load_dwordx4 v[92:95], v[92:93], off offset:576
	s_nop 0
	global_load_dwordx4 v[96:99], v[108:109], off
	global_load_dwordx4 v[100:103], v[108:109], off offset:64
	global_load_dwordx4 v[104:107], v[108:109], off offset:512
	s_nop 0
	global_load_dwordx4 v[108:111], v[108:109], off offset:576
	s_nop 0
	global_load_dwordx4 v[112:115], v[124:125], off
	global_load_dwordx4 v[116:119], v[124:125], off offset:64
	global_load_dwordx4 v[120:123], v[124:125], off offset:512
	s_nop 0
	global_load_dwordx4 v[124:127], v[124:125], off offset:576
	v_lshl_add_u64 v[146:147], s[28:29], 0, v[156:157]
	v_lshl_add_u64 v[156:157], s[28:29], 0, v[158:159]
	v_lshl_add_u64 v[158:159], s[28:29], 0, v[160:161]
	v_lshl_add_u64 v[148:149], s[28:29], 0, v[148:149]
	v_lshl_add_u64 v[146:147], v[146:147], 0, v[144:145]
	v_lshl_add_u64 v[156:157], v[156:157], 0, v[144:145]
	v_lshl_add_u64 v[158:159], v[158:159], 0, v[144:145]
	v_lshl_add_u64 v[144:145], v[148:149], 0, v[144:145]
	s_waitcnt vmcnt(0)
	v_pk_add_f32 v[62:63], v[62:63], v[66:67]
	v_pk_add_f32 v[60:61], v[60:61], v[64:65]
	v_pk_add_f32 v[58:59], v[58:59], v[70:71]
	v_pk_add_f32 v[56:57], v[56:57], v[68:69]
	v_pk_add_f32 v[42:43], v[42:43], v[74:75]
	v_pk_add_f32 v[40:41], v[40:41], v[72:73]
	v_pk_add_f32 v[2:3], v[2:3], v[126:127]
	v_pk_add_f32 v[0:1], v[0:1], v[124:125]
	v_pk_add_f32 v[34:35], v[34:35], v[78:79]
	v_pk_add_f32 v[32:33], v[32:33], v[76:77]
	v_pk_add_f32 v[54:55], v[54:55], v[82:83]
	v_pk_add_f32 v[52:53], v[52:53], v[80:81]
	v_pk_add_f32 v[50:51], v[50:51], v[86:87]
	v_pk_add_f32 v[48:49], v[48:49], v[84:85]
	v_pk_add_f32 v[26:27], v[26:27], v[90:91]
	v_pk_add_f32 v[24:25], v[24:25], v[88:89]
	v_pk_add_f32 v[22:23], v[22:23], v[94:95]
	v_pk_add_f32 v[20:21], v[20:21], v[92:93]
	v_pk_add_f32 v[46:47], v[46:47], v[98:99]
	v_pk_add_f32 v[44:45], v[44:45], v[96:97]
	v_pk_add_f32 v[38:39], v[38:39], v[102:103]
	v_pk_add_f32 v[36:37], v[36:37], v[100:101]
	v_pk_add_f32 v[14:15], v[14:15], v[106:107]
	v_pk_add_f32 v[12:13], v[12:13], v[104:105]
	v_pk_add_f32 v[10:11], v[10:11], v[110:111]
	v_pk_add_f32 v[8:9], v[8:9], v[108:109]
	v_pk_add_f32 v[30:31], v[30:31], v[114:115]
	v_pk_add_f32 v[28:29], v[28:29], v[112:113]
	v_pk_add_f32 v[18:19], v[18:19], v[118:119]
	v_pk_add_f32 v[16:17], v[16:17], v[116:117]
	v_pk_add_f32 v[6:7], v[6:7], v[122:123]
	v_pk_add_f32 v[4:5], v[4:5], v[120:121]
	global_store_dwordx4 v[146:147], v[60:63], off
	global_store_dwordx4 v[146:147], v[56:59], off offset:64
	global_store_dwordx4 v[146:147], v[40:43], off offset:512
	global_store_dwordx4 v[146:147], v[32:35], off offset:576
	global_store_dwordx4 v[156:157], v[52:55], off
	global_store_dwordx4 v[156:157], v[48:51], off offset:64
	global_store_dwordx4 v[156:157], v[24:27], off offset:512
	global_store_dwordx4 v[156:157], v[20:23], off offset:576
	global_store_dwordx4 v[158:159], v[44:47], off
	global_store_dwordx4 v[158:159], v[36:39], off offset:64
	global_store_dwordx4 v[158:159], v[12:15], off offset:512
	global_store_dwordx4 v[158:159], v[8:11], off offset:576
	global_store_dwordx4 v[144:145], v[28:31], off
	global_store_dwordx4 v[144:145], v[16:19], off offset:64
	global_store_dwordx4 v[144:145], v[4:7], off offset:512
	global_store_dwordx4 v[144:145], v[0:3], off offset:576
	s_cmpk_le_u32 s7, 0xff
	s_cbranch_scc1 .Lp5_e1
	s_barrier
.Lp5_e1:
	s_cbranch_vccz .LBB0_696
	s_waitcnt vmcnt(0)
	s_cmpk_gt_u32 s7, 0xff
	s_cbranch_scc1 .LBB0_709
	s_barrier
